# EpiResid epilogues (out-proj / FFN-down prompt) rewritten: per-wave LDS transpose so each residual load/store covers whole 128-B row segments with adjacent lanes (static LDS +18 KB scratch)
# speedup vs baseline: 1.0377x; 1.0170x over previous
; __device__ __forceinline__ unsigned pk(float lo, float hi) { return pg8::cvt_pk_bf16(lo, hi); }
; __device__ __forceinline__ float dot4(f32x4 v) { return (v[0] * v[0] + v[1] * v[1]) + (v[2] * v[2] + v[3] * v[3]); }
;     __device__ __forceinline__ void operator()(const pg8::f32x4 (&acc)[2][2][4][2], const pg8::Unit& u, int wr, int wc, int fr, int fq) const {
;         const int row0 = u.pm * 256 + wr * 64 + fr;
; #pragma unroll
;         for (int ai = 0; ai < 2; ++ai)
; #pragma unroll
;             for (int m = 0; m < 4; ++m) {
;                 const int row = row0 + ai * 128 + m * 16;
;                 const float* xi = (row < MP) ? xin_p + (size_t)row * DM : xin_s + (size_t)(row - MP) * DM;
;                 float sq = 0.f;
; #pragma unroll
;                 for (int bj = 0; bj < 2; ++bj) { const int col = u.pn * 256 + bj * 128 + wc * 32 + 8 * fq;
;                     const f32x4 a0 = *(const f32x4*)(xi + col) + acc[ai][bj][m][0], a1 = *(const f32x4*)(xi + col + 4) + acc[ai][bj][m][1];
;                     *(f32x4*)(xout + (size_t)row * DM + col) = a0; *(f32x4*)(xout + (size_t)row * DM + col + 4) = a1;
;                     u32x4 w; w.x = pk(a0[0], a0[1]); w.y = pk(a0[2], a0[3]); w.z = pk(a1[0], a1[1]); w.w = pk(a1[2], a1[3]);
;                     *(u32x4*)(xb + (size_t)row * DM + col) = w;
;                     sq += dot4(a0) + dot4(a1); }
;                 sq += __shfl_xor(sq, 16); sq += __shfl_xor(sq, 32);
;                 if (fq == 0) atomicAdd(ssout + row, sq);
;             }
;     }
.LBB0_786:
	s_cmp_lt_u32 s74, 64
	s_cselect_b32 s98, s12, s14
	s_cselect_b32 s99, s13, s15
	s_cselect_b32 s100, 0, 0x4000
	v_and_b32_e32 v216, 63, v0
	v_lshrrev_b32_e32 v217, 3, v216
	v_and_b32_e32 v214, 7, v216
	v_and_b32_e32 v138, -16, v154
	v_add_u32_e32 v138, v138, v217
	v_lshl_add_u32 v138, s74, 8, v138
	v_and_b32_e32 v161, -32, v156
	v_lshl_add_u32 v161, v214, 2, v161
	v_lshl_or_b32 v161, s72, 8, v161
	v_lshlrev_b32_e32 v166, 2, v138
	v_lshlrev_b32_e32 v215, 1, v161
	v_lshl_add_u32 v167, v138, 11, v215
	v_lshlrev_b32_e32 v215, 2, v161
	v_lshl_add_u32 v250, v138, 12, v215
	v_subrev_u32_e32 v210, s100, v138
	v_lshl_add_u32 v251, v210, 12, v215
	v_lshrrev_b32_e32 v210, 6, v0
	v_mul_u32_u24_e32 v210, 0x900, v210
	v_add_u32_e32 v210, 0x21000, v210
	v_mul_u32_u24_e32 v212, 0x90, v217
	v_lshl_add_u32 v212, v214, 4, v212
	v_add_u32_e32 v207, v210, v212
	v_and_b32_e32 v212, 15, v216
	v_mul_u32_u24_e32 v212, 0x90, v212
	v_lshrrev_b32_e32 v213, 4, v216
	v_lshl_add_u32 v212, v213, 5, v212
	v_add_u32_e32 v206, v210, v212
	v_add_u32_e32 v209, 0x8000, v251
	global_load_dwordx4 v[146:149], v251, s[98:99]
	global_load_dwordx4 v[150:153], v209, s[98:99]
	global_load_dwordx4 v[162:165], v251, s[98:99] offset:512
	global_load_dwordx4 v[170:173], v209, s[98:99] offset:512
	v_add_u32_e32 v208, 0x10000, v251
	v_add_u32_e32 v209, 0x8000, v208
	global_load_dwordx4 v[174:177], v208, s[98:99]
	global_load_dwordx4 v[178:181], v209, s[98:99]
	global_load_dwordx4 v[182:185], v208, s[98:99] offset:512
	global_load_dwordx4 v[186:189], v209, s[98:99] offset:512
	v_add_u32_e32 v208, 0x20000, v251
	v_add_u32_e32 v209, 0x8000, v208
	global_load_dwordx4 v[190:193], v208, s[98:99]
	global_load_dwordx4 v[194:197], v209, s[98:99]
	global_load_dwordx4 v[198:201], v208, s[98:99] offset:512
	global_load_dwordx4 v[202:205], v209, s[98:99] offset:512
	s_waitcnt vmcnt(8)
	v_add_u32_e32 v211, 0x8000, v250
	v_add_u32_e32 v213, 0x4000, v167
	ds_write_b128 v206, v[126:129]
	ds_write_b128 v206, v[122:125] offset:16
	ds_read_b128 v[126:129], v207
	ds_read_b128 v[122:125], v207 offset:1152
	s_waitcnt lgkmcnt(0)
	v_pk_add_f32 v[126:127], v[126:127], v[146:147]
	v_pk_add_f32 v[128:129], v[128:129], v[148:149]
	v_pk_add_f32 v[122:123], v[122:123], v[150:151]
	v_pk_add_f32 v[124:125], v[124:125], v[152:153]
	global_store_dwordx4 v250, v[126:129], s[16:17]
	global_store_dwordx4 v211, v[122:125], s[16:17]
	v_cvt_pk_bf16_f32 v246, v126, v127
	v_cvt_pk_bf16_f32 v247, v128, v129
	v_cvt_pk_bf16_f32 v248, v122, v123
	v_cvt_pk_bf16_f32 v249, v124, v125
	v_mul_f32_e32 v214, v126, v126
	v_mul_f32_e32 v215, v122, v122
	v_fmac_f32_e32 v214, v127, v127
	v_fmac_f32_e32 v215, v123, v123
	v_fmac_f32_e32 v214, v128, v128
	v_fmac_f32_e32 v215, v124, v124
	v_fmac_f32_e32 v214, v129, v129
	v_fmac_f32_e32 v215, v125, v125
	global_store_dwordx2 v167, v[246:247], s[64:65]
	global_store_dwordx2 v213, v[248:249], s[64:65]
	ds_write_b128 v206, v[118:121]
	ds_write_b128 v206, v[114:117] offset:16
	ds_read_b128 v[118:121], v207
	ds_read_b128 v[114:117], v207 offset:1152
	s_waitcnt lgkmcnt(0)
	v_pk_add_f32 v[118:119], v[118:119], v[162:163]
	v_pk_add_f32 v[120:121], v[120:121], v[164:165]
	v_pk_add_f32 v[114:115], v[114:115], v[170:171]
	v_pk_add_f32 v[116:117], v[116:117], v[172:173]
	global_store_dwordx4 v250, v[118:121], s[16:17] offset:512
	global_store_dwordx4 v211, v[114:117], s[16:17] offset:512
	v_cvt_pk_bf16_f32 v246, v118, v119
	v_cvt_pk_bf16_f32 v247, v120, v121
	v_cvt_pk_bf16_f32 v248, v114, v115
	v_cvt_pk_bf16_f32 v249, v116, v117
	v_fmac_f32_e32 v214, v118, v118
	v_fmac_f32_e32 v215, v114, v114
	v_fmac_f32_e32 v214, v119, v119
	v_fmac_f32_e32 v215, v115, v115
	v_fmac_f32_e32 v214, v120, v120
	v_fmac_f32_e32 v215, v116, v116
	v_fmac_f32_e32 v214, v121, v121
	v_fmac_f32_e32 v215, v117, v117
	global_store_dwordx2 v167, v[246:247], s[64:65] offset:256
	global_store_dwordx2 v213, v[248:249], s[64:65] offset:256
	s_nop 1
	v_add_f32_dpp v214, v214, v214 quad_perm:[1,0,3,2] row_mask:0xf bank_mask:0xf
	v_add_f32_dpp v215, v215, v215 quad_perm:[1,0,3,2] row_mask:0xf bank_mask:0xf
	s_nop 0
	v_add_f32_dpp v214, v214, v214 quad_perm:[2,3,0,1] row_mask:0xf bank_mask:0xf
	v_add_f32_dpp v215, v215, v215 quad_perm:[2,3,0,1] row_mask:0xf bank_mask:0xf
	s_nop 0
	v_add_f32_dpp v214, v214, v214 row_half_mirror row_mask:0xf bank_mask:0xf
	v_add_f32_dpp v215, v215, v215 row_half_mirror row_mask:0xf bank_mask:0xf
	s_nop 0
	s_mov_b32 exec_lo, 0x1010101
	s_mov_b32 exec_hi, 0x1010101
	global_atomic_add_f32 v166, v214, s[10:11]
	global_atomic_add_f32 v166, v215, s[10:11] offset:32
	s_mov_b64 exec, -1
	v_add_u32_e32 v208, 0x30000, v251
	v_add_u32_e32 v209, 0x8000, v208
	global_load_dwordx4 v[146:149], v208, s[98:99]
	global_load_dwordx4 v[150:153], v209, s[98:99]
	global_load_dwordx4 v[162:165], v208, s[98:99] offset:512
	global_load_dwordx4 v[170:173], v209, s[98:99] offset:512
	s_waitcnt vmcnt(18)
	v_add_u32_e32 v210, 0x10000, v250
	v_add_u32_e32 v212, 0x8000, v167
	v_add_u32_e32 v211, 0x8000, v210
	v_add_u32_e32 v213, 0x4000, v212
	ds_write_b128 v206, v[110:113]
	ds_write_b128 v206, v[106:109] offset:16
	ds_read_b128 v[110:113], v207
	ds_read_b128 v[106:109], v207 offset:1152
	s_waitcnt lgkmcnt(0)
; __device__ __forceinline__ unsigned pk(float lo, float hi) { return pg8::cvt_pk_bf16(lo, hi); }
; __device__ __forceinline__ float dot4(f32x4 v) { return (v[0] * v[0] + v[1] * v[1]) + (v[2] * v[2] + v[3] * v[3]); }
;     __device__ __forceinline__ void operator()(const pg8::f32x4 (&acc)[2][2][4][2], const pg8::Unit& u, int wr, int wc, int fr, int fq) const {
;         const int row0 = u.pm * 256 + wr * 64 + fr;
; #pragma unroll
;         for (int ai = 0; ai < 2; ++ai)
; #pragma unroll
;             for (int m = 0; m < 4; ++m) {
;                 const int row = row0 + ai * 128 + m * 16;
;                 const float* xi = (row < MP) ? xin_p + (size_t)row * DM : xin_s + (size_t)(row - MP) * DM;
;                 float sq = 0.f;
; #pragma unroll
;                 for (int bj = 0; bj < 2; ++bj) { const int col = u.pn * 256 + bj * 128 + wc * 32 + 8 * fq;
;                     const f32x4 a0 = *(const f32x4*)(xi + col) + acc[ai][bj][m][0], a1 = *(const f32x4*)(xi + col + 4) + acc[ai][bj][m][1];
;                     *(f32x4*)(xout + (size_t)row * DM + col) = a0; *(f32x4*)(xout + (size_t)row * DM + col + 4) = a1;
;                     u32x4 w; w.x = pk(a0[0], a0[1]); w.y = pk(a0[2], a0[3]); w.z = pk(a1[0], a1[1]); w.w = pk(a1[2], a1[3]);
;                     *(u32x4*)(xb + (size_t)row * DM + col) = w;
;                     sq += dot4(a0) + dot4(a1); }
;                 sq += __shfl_xor(sq, 16); sq += __shfl_xor(sq, 32);
;                 if (fq == 0) atomicAdd(ssout + row, sq);
;             }
;     }
	v_pk_add_f32 v[110:111], v[110:111], v[174:175]
	v_pk_add_f32 v[112:113], v[112:113], v[176:177]
	v_pk_add_f32 v[106:107], v[106:107], v[178:179]
	v_pk_add_f32 v[108:109], v[108:109], v[180:181]
	global_store_dwordx4 v210, v[110:113], s[16:17]
	global_store_dwordx4 v211, v[106:109], s[16:17]
	v_cvt_pk_bf16_f32 v246, v110, v111
	v_cvt_pk_bf16_f32 v247, v112, v113
	v_cvt_pk_bf16_f32 v248, v106, v107
	v_cvt_pk_bf16_f32 v249, v108, v109
	v_mul_f32_e32 v214, v110, v110
	v_mul_f32_e32 v215, v106, v106
	v_fmac_f32_e32 v214, v111, v111
	v_fmac_f32_e32 v215, v107, v107
	v_fmac_f32_e32 v214, v112, v112
	v_fmac_f32_e32 v215, v108, v108
	v_fmac_f32_e32 v214, v113, v113
	v_fmac_f32_e32 v215, v109, v109
	global_store_dwordx2 v212, v[246:247], s[64:65]
	global_store_dwordx2 v213, v[248:249], s[64:65]
	ds_write_b128 v206, v[102:105]
	ds_write_b128 v206, v[98:101] offset:16
	ds_read_b128 v[102:105], v207
	ds_read_b128 v[98:101], v207 offset:1152
	s_waitcnt lgkmcnt(0)
	v_pk_add_f32 v[102:103], v[102:103], v[182:183]
	v_pk_add_f32 v[104:105], v[104:105], v[184:185]
	v_pk_add_f32 v[98:99], v[98:99], v[186:187]
	v_pk_add_f32 v[100:101], v[100:101], v[188:189]
	global_store_dwordx4 v210, v[102:105], s[16:17] offset:512
	global_store_dwordx4 v211, v[98:101], s[16:17] offset:512
	v_cvt_pk_bf16_f32 v246, v102, v103
	v_cvt_pk_bf16_f32 v247, v104, v105
	v_cvt_pk_bf16_f32 v248, v98, v99
	v_cvt_pk_bf16_f32 v249, v100, v101
	v_fmac_f32_e32 v214, v102, v102
	v_fmac_f32_e32 v215, v98, v98
	v_fmac_f32_e32 v214, v103, v103
	v_fmac_f32_e32 v215, v99, v99
	v_fmac_f32_e32 v214, v104, v104
	v_fmac_f32_e32 v215, v100, v100
	v_fmac_f32_e32 v214, v105, v105
	v_fmac_f32_e32 v215, v101, v101
	global_store_dwordx2 v212, v[246:247], s[64:65] offset:256
	global_store_dwordx2 v213, v[248:249], s[64:65] offset:256
	s_nop 1
	v_add_f32_dpp v214, v214, v214 quad_perm:[1,0,3,2] row_mask:0xf bank_mask:0xf
	v_add_f32_dpp v215, v215, v215 quad_perm:[1,0,3,2] row_mask:0xf bank_mask:0xf
	s_nop 0
	v_add_f32_dpp v214, v214, v214 quad_perm:[2,3,0,1] row_mask:0xf bank_mask:0xf
	v_add_f32_dpp v215, v215, v215 quad_perm:[2,3,0,1] row_mask:0xf bank_mask:0xf
	s_nop 0
	v_add_f32_dpp v214, v214, v214 row_half_mirror row_mask:0xf bank_mask:0xf
	v_add_f32_dpp v215, v215, v215 row_half_mirror row_mask:0xf bank_mask:0xf
	s_nop 0
	s_mov_b32 exec_lo, 0x1010101
	s_mov_b32 exec_hi, 0x1010101
	global_atomic_add_f32 v166, v214, s[10:11] offset:64
	global_atomic_add_f32 v166, v215, s[10:11] offset:96
	s_mov_b64 exec, -1
	v_add_u32_e32 v208, 0x80000, v251
	v_add_u32_e32 v209, 0x8000, v208
	global_load_dwordx4 v[174:177], v208, s[98:99]
	global_load_dwordx4 v[178:181], v209, s[98:99]
	global_load_dwordx4 v[182:185], v208, s[98:99] offset:512
	global_load_dwordx4 v[186:189], v209, s[98:99] offset:512
	s_waitcnt vmcnt(28)
	v_add_u32_e32 v210, 0x20000, v250
	v_add_u32_e32 v212, 0x10000, v167
	v_add_u32_e32 v211, 0x8000, v210
	v_add_u32_e32 v213, 0x4000, v212
	ds_write_b128 v206, v[94:97]
	ds_write_b128 v206, v[90:93] offset:16
	ds_read_b128 v[94:97], v207
	ds_read_b128 v[90:93], v207 offset:1152
	s_waitcnt lgkmcnt(0)
	v_pk_add_f32 v[94:95], v[94:95], v[190:191]
	v_pk_add_f32 v[96:97], v[96:97], v[192:193]
	v_pk_add_f32 v[90:91], v[90:91], v[194:195]
	v_pk_add_f32 v[92:93], v[92:93], v[196:197]
	global_store_dwordx4 v210, v[94:97], s[16:17]
	global_store_dwordx4 v211, v[90:93], s[16:17]
	v_cvt_pk_bf16_f32 v246, v94, v95
	v_cvt_pk_bf16_f32 v247, v96, v97
	v_cvt_pk_bf16_f32 v248, v90, v91
	v_cvt_pk_bf16_f32 v249, v92, v93
	v_mul_f32_e32 v214, v94, v94
	v_mul_f32_e32 v215, v90, v90
	v_fmac_f32_e32 v214, v95, v95
	v_fmac_f32_e32 v215, v91, v91
	v_fmac_f32_e32 v214, v96, v96
	v_fmac_f32_e32 v215, v92, v92
	v_fmac_f32_e32 v214, v97, v97
	v_fmac_f32_e32 v215, v93, v93
	global_store_dwordx2 v212, v[246:247], s[64:65]
	global_store_dwordx2 v213, v[248:249], s[64:65]
	ds_write_b128 v206, v[86:89]
	ds_write_b128 v206, v[82:85] offset:16
	ds_read_b128 v[86:89], v207
	ds_read_b128 v[82:85], v207 offset:1152
	s_waitcnt lgkmcnt(0)
	v_pk_add_f32 v[86:87], v[86:87], v[198:199]
	v_pk_add_f32 v[88:89], v[88:89], v[200:201]
	v_pk_add_f32 v[82:83], v[82:83], v[202:203]
	v_pk_add_f32 v[84:85], v[84:85], v[204:205]
	global_store_dwordx4 v210, v[86:89], s[16:17] offset:512
	global_store_dwordx4 v211, v[82:85], s[16:17] offset:512
	v_cvt_pk_bf16_f32 v246, v86, v87
	v_cvt_pk_bf16_f32 v247, v88, v89
	v_cvt_pk_bf16_f32 v248, v82, v83
	v_cvt_pk_bf16_f32 v249, v84, v85
	v_fmac_f32_e32 v214, v86, v86
	v_fmac_f32_e32 v215, v82, v82
	v_fmac_f32_e32 v214, v87, v87
	v_fmac_f32_e32 v215, v83, v83
	v_fmac_f32_e32 v214, v88, v88
	v_fmac_f32_e32 v215, v84, v84
	v_fmac_f32_e32 v214, v89, v89
	v_fmac_f32_e32 v215, v85, v85
	global_store_dwordx2 v212, v[246:247], s[64:65] offset:256
	global_store_dwordx2 v213, v[248:249], s[64:65] offset:256
	s_nop 1
	v_add_f32_dpp v214, v214, v214 quad_perm:[1,0,3,2] row_mask:0xf bank_mask:0xf
	v_add_f32_dpp v215, v215, v215 quad_perm:[1,0,3,2] row_mask:0xf bank_mask:0xf
	s_nop 0
	v_add_f32_dpp v214, v214, v214 quad_perm:[2,3,0,1] row_mask:0xf bank_mask:0xf
	v_add_f32_dpp v215, v215, v215 quad_perm:[2,3,0,1] row_mask:0xf bank_mask:0xf
	s_nop 0
	v_add_f32_dpp v214, v214, v214 row_half_mirror row_mask:0xf bank_mask:0xf
	v_add_f32_dpp v215, v215, v215 row_half_mirror row_mask:0xf bank_mask:0xf
	s_nop 0
	s_mov_b32 exec_lo, 0x1010101
	s_mov_b32 exec_hi, 0x1010101
	global_atomic_add_f32 v166, v214, s[10:11] offset:128
	global_atomic_add_f32 v166, v215, s[10:11] offset:160
	s_mov_b64 exec, -1
	v_add_u32_e32 v208, 0x90000, v251
	v_add_u32_e32 v209, 0x8000, v208
	global_load_dwordx4 v[190:193], v208, s[98:99]
	global_load_dwordx4 v[194:197], v209, s[98:99]
	global_load_dwordx4 v[198:201], v208, s[98:99] offset:512
	global_load_dwordx4 v[202:205], v209, s[98:99] offset:512
	s_waitcnt vmcnt(28)
; __device__ __forceinline__ unsigned pk(float lo, float hi) { return pg8::cvt_pk_bf16(lo, hi); }
; __device__ __forceinline__ float dot4(f32x4 v) { return (v[0] * v[0] + v[1] * v[1]) + (v[2] * v[2] + v[3] * v[3]); }
;     __device__ __forceinline__ void operator()(const pg8::f32x4 (&acc)[2][2][4][2], const pg8::Unit& u, int wr, int wc, int fr, int fq) const {
;         const int row0 = u.pm * 256 + wr * 64 + fr;
; #pragma unroll
;         for (int ai = 0; ai < 2; ++ai)
; #pragma unroll
;             for (int m = 0; m < 4; ++m) {
;                 const int row = row0 + ai * 128 + m * 16;
;                 const float* xi = (row < MP) ? xin_p + (size_t)row * DM : xin_s + (size_t)(row - MP) * DM;
;                 float sq = 0.f;
; #pragma unroll
;                 for (int bj = 0; bj < 2; ++bj) { const int col = u.pn * 256 + bj * 128 + wc * 32 + 8 * fq;
;                     const f32x4 a0 = *(const f32x4*)(xi + col) + acc[ai][bj][m][0], a1 = *(const f32x4*)(xi + col + 4) + acc[ai][bj][m][1];
;                     *(f32x4*)(xout + (size_t)row * DM + col) = a0; *(f32x4*)(xout + (size_t)row * DM + col + 4) = a1;
;                     u32x4 w; w.x = pk(a0[0], a0[1]); w.y = pk(a0[2], a0[3]); w.z = pk(a1[0], a1[1]); w.w = pk(a1[2], a1[3]);
;                     *(u32x4*)(xb + (size_t)row * DM + col) = w;
;                     sq += dot4(a0) + dot4(a1); }
;                 sq += __shfl_xor(sq, 16); sq += __shfl_xor(sq, 32);
;                 if (fq == 0) atomicAdd(ssout + row, sq);
;             }
;     }
	v_add_u32_e32 v210, 0x30000, v250
	v_add_u32_e32 v212, 0x18000, v167
	v_add_u32_e32 v211, 0x8000, v210
	v_add_u32_e32 v213, 0x4000, v212
	ds_write_b128 v206, v[78:81]
	ds_write_b128 v206, v[74:77] offset:16
	ds_read_b128 v[78:81], v207
	ds_read_b128 v[74:77], v207 offset:1152
	s_waitcnt lgkmcnt(0)
	v_pk_add_f32 v[78:79], v[78:79], v[146:147]
	v_pk_add_f32 v[80:81], v[80:81], v[148:149]
	v_pk_add_f32 v[74:75], v[74:75], v[150:151]
	v_pk_add_f32 v[76:77], v[76:77], v[152:153]
	global_store_dwordx4 v210, v[78:81], s[16:17]
	global_store_dwordx4 v211, v[74:77], s[16:17]
	v_cvt_pk_bf16_f32 v246, v78, v79
	v_cvt_pk_bf16_f32 v247, v80, v81
	v_cvt_pk_bf16_f32 v248, v74, v75
	v_cvt_pk_bf16_f32 v249, v76, v77
	v_mul_f32_e32 v214, v78, v78
	v_mul_f32_e32 v215, v74, v74
	v_fmac_f32_e32 v214, v79, v79
	v_fmac_f32_e32 v215, v75, v75
	v_fmac_f32_e32 v214, v80, v80
	v_fmac_f32_e32 v215, v76, v76
	v_fmac_f32_e32 v214, v81, v81
	v_fmac_f32_e32 v215, v77, v77
	global_store_dwordx2 v212, v[246:247], s[64:65]
	global_store_dwordx2 v213, v[248:249], s[64:65]
	ds_write_b128 v206, v[70:73]
	ds_write_b128 v206, v[66:69] offset:16
	ds_read_b128 v[70:73], v207
	ds_read_b128 v[66:69], v207 offset:1152
	s_waitcnt lgkmcnt(0)
	v_pk_add_f32 v[70:71], v[70:71], v[162:163]
	v_pk_add_f32 v[72:73], v[72:73], v[164:165]
	v_pk_add_f32 v[66:67], v[66:67], v[170:171]
	v_pk_add_f32 v[68:69], v[68:69], v[172:173]
	global_store_dwordx4 v210, v[70:73], s[16:17] offset:512
	global_store_dwordx4 v211, v[66:69], s[16:17] offset:512
	v_cvt_pk_bf16_f32 v246, v70, v71
	v_cvt_pk_bf16_f32 v247, v72, v73
	v_cvt_pk_bf16_f32 v248, v66, v67
	v_cvt_pk_bf16_f32 v249, v68, v69
	v_fmac_f32_e32 v214, v70, v70
	v_fmac_f32_e32 v215, v66, v66
	v_fmac_f32_e32 v214, v71, v71
	v_fmac_f32_e32 v215, v67, v67
	v_fmac_f32_e32 v214, v72, v72
	v_fmac_f32_e32 v215, v68, v68
	v_fmac_f32_e32 v214, v73, v73
	v_fmac_f32_e32 v215, v69, v69
	global_store_dwordx2 v212, v[246:247], s[64:65] offset:256
	global_store_dwordx2 v213, v[248:249], s[64:65] offset:256
	s_nop 1
	v_add_f32_dpp v214, v214, v214 quad_perm:[1,0,3,2] row_mask:0xf bank_mask:0xf
	v_add_f32_dpp v215, v215, v215 quad_perm:[1,0,3,2] row_mask:0xf bank_mask:0xf
	s_nop 0
	v_add_f32_dpp v214, v214, v214 quad_perm:[2,3,0,1] row_mask:0xf bank_mask:0xf
	v_add_f32_dpp v215, v215, v215 quad_perm:[2,3,0,1] row_mask:0xf bank_mask:0xf
	s_nop 0
	v_add_f32_dpp v214, v214, v214 row_half_mirror row_mask:0xf bank_mask:0xf
	v_add_f32_dpp v215, v215, v215 row_half_mirror row_mask:0xf bank_mask:0xf
	s_nop 0
	s_mov_b32 exec_lo, 0x1010101
	s_mov_b32 exec_hi, 0x1010101
	global_atomic_add_f32 v166, v214, s[10:11] offset:192
	global_atomic_add_f32 v166, v215, s[10:11] offset:224
	s_mov_b64 exec, -1
	v_add_u32_e32 v208, 0xa0000, v251
	v_add_u32_e32 v209, 0x8000, v208
	global_load_dwordx4 v[146:149], v208, s[98:99]
	global_load_dwordx4 v[150:153], v209, s[98:99]
	global_load_dwordx4 v[162:165], v208, s[98:99] offset:512
	global_load_dwordx4 v[170:173], v209, s[98:99] offset:512
	s_waitcnt vmcnt(28)
	v_add_u32_e32 v210, 0x80000, v250
	v_add_u32_e32 v212, 0x40000, v167
	v_add_u32_e32 v211, 0x8000, v210
	v_add_u32_e32 v213, 0x4000, v212
	ds_write_b128 v206, v[62:65]
	ds_write_b128 v206, v[58:61] offset:16
	ds_read_b128 v[62:65], v207
	ds_read_b128 v[58:61], v207 offset:1152
	s_waitcnt lgkmcnt(0)
	v_pk_add_f32 v[62:63], v[62:63], v[174:175]
	v_pk_add_f32 v[64:65], v[64:65], v[176:177]
	v_pk_add_f32 v[58:59], v[58:59], v[178:179]
	v_pk_add_f32 v[60:61], v[60:61], v[180:181]
	global_store_dwordx4 v210, v[62:65], s[16:17]
	global_store_dwordx4 v211, v[58:61], s[16:17]
	v_cvt_pk_bf16_f32 v246, v62, v63
	v_cvt_pk_bf16_f32 v247, v64, v65
	v_cvt_pk_bf16_f32 v248, v58, v59
	v_cvt_pk_bf16_f32 v249, v60, v61
	v_mul_f32_e32 v214, v62, v62
	v_mul_f32_e32 v215, v58, v58
	v_fmac_f32_e32 v214, v63, v63
	v_fmac_f32_e32 v215, v59, v59
	v_fmac_f32_e32 v214, v64, v64
	v_fmac_f32_e32 v215, v60, v60
	v_fmac_f32_e32 v214, v65, v65
	v_fmac_f32_e32 v215, v61, v61
	global_store_dwordx2 v212, v[246:247], s[64:65]
	global_store_dwordx2 v213, v[248:249], s[64:65]
	ds_write_b128 v206, v[54:57]
	ds_write_b128 v206, v[50:53] offset:16
	ds_read_b128 v[54:57], v207
	ds_read_b128 v[50:53], v207 offset:1152
	s_waitcnt lgkmcnt(0)
	v_pk_add_f32 v[54:55], v[54:55], v[182:183]
	v_pk_add_f32 v[56:57], v[56:57], v[184:185]
	v_pk_add_f32 v[50:51], v[50:51], v[186:187]
	v_pk_add_f32 v[52:53], v[52:53], v[188:189]
	global_store_dwordx4 v210, v[54:57], s[16:17] offset:512
	global_store_dwordx4 v211, v[50:53], s[16:17] offset:512
	v_cvt_pk_bf16_f32 v246, v54, v55
	v_cvt_pk_bf16_f32 v247, v56, v57
	v_cvt_pk_bf16_f32 v248, v50, v51
	v_cvt_pk_bf16_f32 v249, v52, v53
	v_fmac_f32_e32 v214, v54, v54
	v_fmac_f32_e32 v215, v50, v50
	v_fmac_f32_e32 v214, v55, v55
	v_fmac_f32_e32 v215, v51, v51
	v_fmac_f32_e32 v214, v56, v56
	v_fmac_f32_e32 v215, v52, v52
	v_fmac_f32_e32 v214, v57, v57
	v_fmac_f32_e32 v215, v53, v53
	global_store_dwordx2 v212, v[246:247], s[64:65] offset:256
	global_store_dwordx2 v213, v[248:249], s[64:65] offset:256
	s_nop 1
	v_add_f32_dpp v214, v214, v214 quad_perm:[1,0,3,2] row_mask:0xf bank_mask:0xf
	v_add_f32_dpp v215, v215, v215 quad_perm:[1,0,3,2] row_mask:0xf bank_mask:0xf
	s_nop 0
	v_add_f32_dpp v214, v214, v214 quad_perm:[2,3,0,1] row_mask:0xf bank_mask:0xf
	v_add_f32_dpp v215, v215, v215 quad_perm:[2,3,0,1] row_mask:0xf bank_mask:0xf
	s_nop 0
	v_add_f32_dpp v214, v214, v214 row_half_mirror row_mask:0xf bank_mask:0xf
	v_add_f32_dpp v215, v215, v215 row_half_mirror row_mask:0xf bank_mask:0xf
	s_nop 0
	s_mov_b32 exec_lo, 0x1010101
	s_mov_b32 exec_hi, 0x1010101
	global_atomic_add_f32 v166, v214, s[10:11] offset:512
	global_atomic_add_f32 v166, v215, s[10:11] offset:544
	s_mov_b64 exec, -1
	v_add_u32_e32 v208, 0xb0000, v251
	v_add_u32_e32 v209, 0x8000, v208
	global_load_dwordx4 v[174:177], v208, s[98:99]
	global_load_dwordx4 v[178:181], v209, s[98:99]
	global_load_dwordx4 v[182:185], v208, s[98:99] offset:512
	global_load_dwordx4 v[186:189], v209, s[98:99] offset:512
	s_waitcnt vmcnt(28)
; __device__ __forceinline__ unsigned pk(float lo, float hi) { return pg8::cvt_pk_bf16(lo, hi); }
; __device__ __forceinline__ float dot4(f32x4 v) { return (v[0] * v[0] + v[1] * v[1]) + (v[2] * v[2] + v[3] * v[3]); }
;     __device__ __forceinline__ void operator()(const pg8::f32x4 (&acc)[2][2][4][2], const pg8::Unit& u, int wr, int wc, int fr, int fq) const {
;         const int row0 = u.pm * 256 + wr * 64 + fr;
; #pragma unroll
;         for (int ai = 0; ai < 2; ++ai)
; #pragma unroll
;             for (int m = 0; m < 4; ++m) {
;                 const int row = row0 + ai * 128 + m * 16;
;                 const float* xi = (row < MP) ? xin_p + (size_t)row * DM : xin_s + (size_t)(row - MP) * DM;
;                 float sq = 0.f;
; #pragma unroll
;                 for (int bj = 0; bj < 2; ++bj) { const int col = u.pn * 256 + bj * 128 + wc * 32 + 8 * fq;
;                     const f32x4 a0 = *(const f32x4*)(xi + col) + acc[ai][bj][m][0], a1 = *(const f32x4*)(xi + col + 4) + acc[ai][bj][m][1];
;                     *(f32x4*)(xout + (size_t)row * DM + col) = a0; *(f32x4*)(xout + (size_t)row * DM + col + 4) = a1;
;                     u32x4 w; w.x = pk(a0[0], a0[1]); w.y = pk(a0[2], a0[3]); w.z = pk(a1[0], a1[1]); w.w = pk(a1[2], a1[3]);
;                     *(u32x4*)(xb + (size_t)row * DM + col) = w;
;                     sq += dot4(a0) + dot4(a1); }
;                 sq += __shfl_xor(sq, 16); sq += __shfl_xor(sq, 32);
;                 if (fq == 0) atomicAdd(ssout + row, sq);
;             }
;     }
	v_add_u32_e32 v210, 0x90000, v250
	v_add_u32_e32 v212, 0x48000, v167
	v_add_u32_e32 v211, 0x8000, v210
	v_add_u32_e32 v213, 0x4000, v212
	ds_write_b128 v206, v[46:49]
	ds_write_b128 v206, v[42:45] offset:16
	ds_read_b128 v[46:49], v207
	ds_read_b128 v[42:45], v207 offset:1152
	s_waitcnt lgkmcnt(0)
	v_pk_add_f32 v[46:47], v[46:47], v[190:191]
	v_pk_add_f32 v[48:49], v[48:49], v[192:193]
	v_pk_add_f32 v[42:43], v[42:43], v[194:195]
	v_pk_add_f32 v[44:45], v[44:45], v[196:197]
	global_store_dwordx4 v210, v[46:49], s[16:17]
	global_store_dwordx4 v211, v[42:45], s[16:17]
	v_cvt_pk_bf16_f32 v246, v46, v47
	v_cvt_pk_bf16_f32 v247, v48, v49
	v_cvt_pk_bf16_f32 v248, v42, v43
	v_cvt_pk_bf16_f32 v249, v44, v45
	v_mul_f32_e32 v214, v46, v46
	v_mul_f32_e32 v215, v42, v42
	v_fmac_f32_e32 v214, v47, v47
	v_fmac_f32_e32 v215, v43, v43
	v_fmac_f32_e32 v214, v48, v48
	v_fmac_f32_e32 v215, v44, v44
	v_fmac_f32_e32 v214, v49, v49
	v_fmac_f32_e32 v215, v45, v45
	global_store_dwordx2 v212, v[246:247], s[64:65]
	global_store_dwordx2 v213, v[248:249], s[64:65]
	ds_write_b128 v206, v[38:41]
	ds_write_b128 v206, v[34:37] offset:16
	ds_read_b128 v[38:41], v207
	ds_read_b128 v[34:37], v207 offset:1152
	s_waitcnt lgkmcnt(0)
	v_pk_add_f32 v[38:39], v[38:39], v[198:199]
	v_pk_add_f32 v[40:41], v[40:41], v[200:201]
	v_pk_add_f32 v[34:35], v[34:35], v[202:203]
	v_pk_add_f32 v[36:37], v[36:37], v[204:205]
	global_store_dwordx4 v210, v[38:41], s[16:17] offset:512
	global_store_dwordx4 v211, v[34:37], s[16:17] offset:512
	v_cvt_pk_bf16_f32 v246, v38, v39
	v_cvt_pk_bf16_f32 v247, v40, v41
	v_cvt_pk_bf16_f32 v248, v34, v35
	v_cvt_pk_bf16_f32 v249, v36, v37
	v_fmac_f32_e32 v214, v38, v38
	v_fmac_f32_e32 v215, v34, v34
	v_fmac_f32_e32 v214, v39, v39
	v_fmac_f32_e32 v215, v35, v35
	v_fmac_f32_e32 v214, v40, v40
	v_fmac_f32_e32 v215, v36, v36
	v_fmac_f32_e32 v214, v41, v41
	v_fmac_f32_e32 v215, v37, v37
	global_store_dwordx2 v212, v[246:247], s[64:65] offset:256
	global_store_dwordx2 v213, v[248:249], s[64:65] offset:256
	s_nop 1
	v_add_f32_dpp v214, v214, v214 quad_perm:[1,0,3,2] row_mask:0xf bank_mask:0xf
	v_add_f32_dpp v215, v215, v215 quad_perm:[1,0,3,2] row_mask:0xf bank_mask:0xf
	s_nop 0
	v_add_f32_dpp v214, v214, v214 quad_perm:[2,3,0,1] row_mask:0xf bank_mask:0xf
	v_add_f32_dpp v215, v215, v215 quad_perm:[2,3,0,1] row_mask:0xf bank_mask:0xf
	s_nop 0
	v_add_f32_dpp v214, v214, v214 row_half_mirror row_mask:0xf bank_mask:0xf
	v_add_f32_dpp v215, v215, v215 row_half_mirror row_mask:0xf bank_mask:0xf
	s_nop 0
	s_mov_b32 exec_lo, 0x1010101
	s_mov_b32 exec_hi, 0x1010101
	global_atomic_add_f32 v166, v214, s[10:11] offset:576
	global_atomic_add_f32 v166, v215, s[10:11] offset:608
	s_mov_b64 exec, -1
	s_waitcnt vmcnt(24)
	v_add_u32_e32 v210, 0xa0000, v250
	v_add_u32_e32 v212, 0x50000, v167
	v_add_u32_e32 v211, 0x8000, v210
	v_add_u32_e32 v213, 0x4000, v212
	ds_write_b128 v206, v[30:33]
	ds_write_b128 v206, v[26:29] offset:16
	ds_read_b128 v[30:33], v207
	ds_read_b128 v[26:29], v207 offset:1152
	s_waitcnt lgkmcnt(0)
	v_pk_add_f32 v[30:31], v[30:31], v[146:147]
	v_pk_add_f32 v[32:33], v[32:33], v[148:149]
	v_pk_add_f32 v[26:27], v[26:27], v[150:151]
	v_pk_add_f32 v[28:29], v[28:29], v[152:153]
	global_store_dwordx4 v210, v[30:33], s[16:17]
	global_store_dwordx4 v211, v[26:29], s[16:17]
	v_cvt_pk_bf16_f32 v246, v30, v31
	v_cvt_pk_bf16_f32 v247, v32, v33
	v_cvt_pk_bf16_f32 v248, v26, v27
	v_cvt_pk_bf16_f32 v249, v28, v29
	v_mul_f32_e32 v214, v30, v30
	v_mul_f32_e32 v215, v26, v26
	v_fmac_f32_e32 v214, v31, v31
	v_fmac_f32_e32 v215, v27, v27
	v_fmac_f32_e32 v214, v32, v32
	v_fmac_f32_e32 v215, v28, v28
	v_fmac_f32_e32 v214, v33, v33
	v_fmac_f32_e32 v215, v29, v29
	global_store_dwordx2 v212, v[246:247], s[64:65]
	global_store_dwordx2 v213, v[248:249], s[64:65]
	ds_write_b128 v206, v[22:25]
	ds_write_b128 v206, v[18:21] offset:16
	ds_read_b128 v[22:25], v207
	ds_read_b128 v[18:21], v207 offset:1152
	s_waitcnt lgkmcnt(0)
; #define PG8_BAR __builtin_amdgcn_s_barrier()
; __device__ __forceinline__ unsigned pk(float lo, float hi) { return pg8::cvt_pk_bf16(lo, hi); }
; __device__ __forceinline__ float dot4(f32x4 v) { return (v[0] * v[0] + v[1] * v[1]) + (v[2] * v[2] + v[3] * v[3]); }
; template <class Epi, class Sched, bool ALIGN_EPI = false, bool SP2 = false>
; __device__ __forceinline__ void gemm_phase(PG8_LAS unsigned char* lds, const Gemm g, const Sched& S, const Epi& E) {
;     ...
;         if (!has_next) break;
; #pragma unroll
;         for (int a = 0; a < 2; ++a)
; #pragma unroll
;             for (int b = 0; b < 2; ++b)
; #pragma unroll
;                 for (int m = 0; m < 4; ++m)
; #pragma unroll
;                     for (int n = 0; n < 2; ++n) acc[a][b][m][n] = (f32x4){0.f, 0.f, 0.f, 0.f};
;         cur = nxt; cA = nA; cB = nB; ++ui;
;         if constexpr (ALIGN_EPI) { if (wr == 1) PG8_BAR; }
;     }
;     __device__ __forceinline__ void operator()(const pg8::f32x4 (&acc)[2][2][4][2], const pg8::Unit& u, int wr, int wc, int fr, int fq) const {
;     ...
;             for (int m = 0; m < 4; ++m) {
;                 const int row = row0 + ai * 128 + m * 16;
;                 const float* xi = (row < MP) ? xin_p + (size_t)row * DM : xin_s + (size_t)(row - MP) * DM;
;                 float sq = 0.f;
; #pragma unroll
;                 for (int bj = 0; bj < 2; ++bj) { const int col = u.pn * 256 + bj * 128 + wc * 32 + 8 * fq;
;                     const f32x4 a0 = *(const f32x4*)(xi + col) + acc[ai][bj][m][0], a1 = *(const f32x4*)(xi + col + 4) + acc[ai][bj][m][1];
;                     *(f32x4*)(xout + (size_t)row * DM + col) = a0; *(f32x4*)(xout + (size_t)row * DM + col + 4) = a1;
;                     u32x4 w; w.x = pk(a0[0], a0[1]); w.y = pk(a0[2], a0[3]); w.z = pk(a1[0], a1[1]); w.w = pk(a1[2], a1[3]);
;                     *(u32x4*)(xb + (size_t)row * DM + col) = w;
;                     sq += dot4(a0) + dot4(a1); }
;                 sq += __shfl_xor(sq, 16); sq += __shfl_xor(sq, 32);
;                 if (fq == 0) atomicAdd(ssout + row, sq);
;             }
;     }
	v_pk_add_f32 v[22:23], v[22:23], v[162:163]
	v_pk_add_f32 v[24:25], v[24:25], v[164:165]
	v_pk_add_f32 v[18:19], v[18:19], v[170:171]
	v_pk_add_f32 v[20:21], v[20:21], v[172:173]
	global_store_dwordx4 v210, v[22:25], s[16:17] offset:512
	global_store_dwordx4 v211, v[18:21], s[16:17] offset:512
	v_cvt_pk_bf16_f32 v246, v22, v23
	v_cvt_pk_bf16_f32 v247, v24, v25
	v_cvt_pk_bf16_f32 v248, v18, v19
	v_cvt_pk_bf16_f32 v249, v20, v21
	v_fmac_f32_e32 v214, v22, v22
	v_fmac_f32_e32 v215, v18, v18
	v_fmac_f32_e32 v214, v23, v23
	v_fmac_f32_e32 v215, v19, v19
	v_fmac_f32_e32 v214, v24, v24
	v_fmac_f32_e32 v215, v20, v20
	v_fmac_f32_e32 v214, v25, v25
	v_fmac_f32_e32 v215, v21, v21
	global_store_dwordx2 v212, v[246:247], s[64:65] offset:256
	global_store_dwordx2 v213, v[248:249], s[64:65] offset:256
	s_nop 1
	v_add_f32_dpp v214, v214, v214 quad_perm:[1,0,3,2] row_mask:0xf bank_mask:0xf
	v_add_f32_dpp v215, v215, v215 quad_perm:[1,0,3,2] row_mask:0xf bank_mask:0xf
	s_nop 0
	v_add_f32_dpp v214, v214, v214 quad_perm:[2,3,0,1] row_mask:0xf bank_mask:0xf
	v_add_f32_dpp v215, v215, v215 quad_perm:[2,3,0,1] row_mask:0xf bank_mask:0xf
	s_nop 0
	v_add_f32_dpp v214, v214, v214 row_half_mirror row_mask:0xf bank_mask:0xf
	v_add_f32_dpp v215, v215, v215 row_half_mirror row_mask:0xf bank_mask:0xf
	s_nop 0
	s_mov_b32 exec_lo, 0x1010101
	s_mov_b32 exec_hi, 0x1010101
	global_atomic_add_f32 v166, v214, s[10:11] offset:640
	global_atomic_add_f32 v166, v215, s[10:11] offset:672
	s_mov_b64 exec, -1
	s_waitcnt vmcnt(20)
	v_add_u32_e32 v210, 0xb0000, v250
	v_add_u32_e32 v212, 0x58000, v167
	v_add_u32_e32 v211, 0x8000, v210
	v_add_u32_e32 v213, 0x4000, v212
	ds_write_b128 v206, v[14:17]
	ds_write_b128 v206, v[10:13] offset:16
	ds_read_b128 v[14:17], v207
	ds_read_b128 v[10:13], v207 offset:1152
	s_waitcnt lgkmcnt(0)
	v_pk_add_f32 v[14:15], v[14:15], v[174:175]
	v_pk_add_f32 v[16:17], v[16:17], v[176:177]
	v_pk_add_f32 v[10:11], v[10:11], v[178:179]
	v_pk_add_f32 v[12:13], v[12:13], v[180:181]
	global_store_dwordx4 v210, v[14:17], s[16:17]
	global_store_dwordx4 v211, v[10:13], s[16:17]
	v_cvt_pk_bf16_f32 v246, v14, v15
	v_cvt_pk_bf16_f32 v247, v16, v17
	v_cvt_pk_bf16_f32 v248, v10, v11
	v_cvt_pk_bf16_f32 v249, v12, v13
	v_mul_f32_e32 v214, v14, v14
	v_mul_f32_e32 v215, v10, v10
	v_fmac_f32_e32 v214, v15, v15
	v_fmac_f32_e32 v215, v11, v11
	v_fmac_f32_e32 v214, v16, v16
	v_fmac_f32_e32 v215, v12, v12
	v_fmac_f32_e32 v214, v17, v17
	v_fmac_f32_e32 v215, v13, v13
	global_store_dwordx2 v212, v[246:247], s[64:65]
	global_store_dwordx2 v213, v[248:249], s[64:65]
	ds_write_b128 v206, v[6:9]
	ds_write_b128 v206, v[2:5] offset:16
	ds_read_b128 v[6:9], v207
	ds_read_b128 v[2:5], v207 offset:1152
	s_waitcnt lgkmcnt(0)
	v_pk_add_f32 v[6:7], v[6:7], v[182:183]
	v_pk_add_f32 v[8:9], v[8:9], v[184:185]
	v_pk_add_f32 v[2:3], v[2:3], v[186:187]
	v_pk_add_f32 v[4:5], v[4:5], v[188:189]
	global_store_dwordx4 v210, v[6:9], s[16:17] offset:512
	global_store_dwordx4 v211, v[2:5], s[16:17] offset:512
	v_cvt_pk_bf16_f32 v246, v6, v7
	v_cvt_pk_bf16_f32 v247, v8, v9
	v_cvt_pk_bf16_f32 v248, v2, v3
	v_cvt_pk_bf16_f32 v249, v4, v5
	v_fmac_f32_e32 v214, v6, v6
	v_fmac_f32_e32 v215, v2, v2
	v_fmac_f32_e32 v214, v7, v7
	v_fmac_f32_e32 v215, v3, v3
	v_fmac_f32_e32 v214, v8, v8
	v_fmac_f32_e32 v215, v4, v4
	v_fmac_f32_e32 v214, v9, v9
	v_fmac_f32_e32 v215, v5, v5
	global_store_dwordx2 v212, v[246:247], s[64:65] offset:256
	global_store_dwordx2 v213, v[248:249], s[64:65] offset:256
	s_nop 1
	v_add_f32_dpp v214, v214, v214 quad_perm:[1,0,3,2] row_mask:0xf bank_mask:0xf
	v_add_f32_dpp v215, v215, v215 quad_perm:[1,0,3,2] row_mask:0xf bank_mask:0xf
	s_nop 0
	v_add_f32_dpp v214, v214, v214 quad_perm:[2,3,0,1] row_mask:0xf bank_mask:0xf
	v_add_f32_dpp v215, v215, v215 quad_perm:[2,3,0,1] row_mask:0xf bank_mask:0xf
	s_nop 0
	v_add_f32_dpp v214, v214, v214 row_half_mirror row_mask:0xf bank_mask:0xf
	v_add_f32_dpp v215, v215, v215 row_half_mirror row_mask:0xf bank_mask:0xf
	s_nop 0
	s_mov_b32 exec_lo, 0x1010101
	s_mov_b32 exec_hi, 0x1010101
	global_atomic_add_f32 v166, v214, s[10:11] offset:704
	global_atomic_add_f32 v166, v215, s[10:11] offset:736
	s_mov_b64 exec, -1
	s_andn2_b64 vcc, exec, s[4:5]
	s_mov_b64 s[4:5], -1
	s_cbranch_vccnz .LBB0_779
	s_andn2_b64 vcc, exec, s[8:9]
	s_cbranch_vccnz .LBB0_778
	s_barrier
	s_branch .LBB0_778

; __device__ __forceinline__ unsigned pk(float lo, float hi) { return pg8::cvt_pk_bf16(lo, hi); }
; __device__ __forceinline__ float dot4(f32x4 v) { return (v[0] * v[0] + v[1] * v[1]) + (v[2] * v[2] + v[3] * v[3]); }
;     __device__ __forceinline__ void operator()(const pg8::f32x4 (&acc)[2][2][4][2], const pg8::Unit& u, int wr, int wc, int fr, int fq) const {
;         const int row0 = u.pm * 256 + wr * 64 + fr;
; #pragma unroll
;         for (int ai = 0; ai < 2; ++ai)
; #pragma unroll
;             for (int m = 0; m < 4; ++m) {
;                 const int row = row0 + ai * 128 + m * 16;
;                 const float* xi = (row < MP) ? xin_p + (size_t)row * DM : xin_s + (size_t)(row - MP) * DM;
;                 float sq = 0.f;
; #pragma unroll
;                 for (int bj = 0; bj < 2; ++bj) { const int col = u.pn * 256 + bj * 128 + wc * 32 + 8 * fq;
;                     const f32x4 a0 = *(const f32x4*)(xi + col) + acc[ai][bj][m][0], a1 = *(const f32x4*)(xi + col + 4) + acc[ai][bj][m][1];
;                     *(f32x4*)(xout + (size_t)row * DM + col) = a0; *(f32x4*)(xout + (size_t)row * DM + col + 4) = a1;
;                     u32x4 w; w.x = pk(a0[0], a0[1]); w.y = pk(a0[2], a0[3]); w.z = pk(a1[0], a1[1]); w.w = pk(a1[2], a1[3]);
;                     *(u32x4*)(xb + (size_t)row * DM + col) = w;
;                     sq += dot4(a0) + dot4(a1); }
;                 sq += __shfl_xor(sq, 16); sq += __shfl_xor(sq, 32);
;                 if (fq == 0) atomicAdd(ssout + row, sq);
;             }
;     }
.LBB0_1140:
	s_cmp_lt_u32 s72, 64
	s_cselect_b32 s98, s16, s8
	s_cselect_b32 s99, s17, s9
	s_cselect_b32 s100, 0, 0x4000
	v_and_b32_e32 v231, 63, v0
	v_lshrrev_b32_e32 v232, 3, v231
	v_and_b32_e32 v229, 7, v231
	v_and_b32_e32 v183, -16, v163
	v_add_u32_e32 v183, v183, v232
	v_lshl_add_u32 v183, s72, 8, v183
	v_and_b32_e32 v216, -32, v164
	v_lshl_add_u32 v216, v229, 2, v216
	v_lshl_or_b32 v216, s71, 8, v216
	v_lshlrev_b32_e32 v217, 2, v183
	v_lshlrev_b32_e32 v230, 1, v216
	v_lshl_add_u32 v218, v183, 11, v230
	v_lshlrev_b32_e32 v230, 2, v216
	v_lshl_add_u32 v219, v183, 12, v230
	v_subrev_u32_e32 v225, s100, v183
	v_lshl_add_u32 v220, v225, 12, v230
	v_lshrrev_b32_e32 v225, 6, v0
	v_mul_u32_u24_e32 v225, 0x900, v225
	v_add_u32_e32 v225, 0x21000, v225
	v_mul_u32_u24_e32 v227, 0x90, v232
	v_lshl_add_u32 v227, v229, 4, v227
	v_add_u32_e32 v222, v225, v227
	v_and_b32_e32 v227, 15, v231
	v_mul_u32_u24_e32 v227, 0x90, v227
	v_lshrrev_b32_e32 v228, 4, v231
	v_lshl_add_u32 v227, v228, 5, v227
	v_add_u32_e32 v221, v225, v227
	v_add_u32_e32 v224, 0x8000, v220
	global_load_dwordx4 v[184:187], v220, s[98:99]
	global_load_dwordx4 v[188:191], v224, s[98:99]
	global_load_dwordx4 v[192:195], v220, s[98:99] offset:512
	global_load_dwordx4 v[196:199], v224, s[98:99] offset:512
	v_add_u32_e32 v223, 0x10000, v220
	v_add_u32_e32 v224, 0x8000, v223
	global_load_dwordx4 v[200:203], v223, s[98:99]
	global_load_dwordx4 v[204:207], v224, s[98:99]
	global_load_dwordx4 v[208:211], v223, s[98:99] offset:512
	global_load_dwordx4 v[212:215], v224, s[98:99] offset:512
	s_waitcnt vmcnt(4)
	v_add_u32_e32 v226, 0x8000, v219
	v_add_u32_e32 v228, 0x4000, v218
	ds_write_b128 v221, v[126:129]
	ds_write_b128 v221, v[122:125] offset:16
	ds_read_b128 v[126:129], v222
	ds_read_b128 v[122:125], v222 offset:1152
	s_waitcnt lgkmcnt(0)
	v_pk_add_f32 v[126:127], v[126:127], v[184:185]
	v_pk_add_f32 v[128:129], v[128:129], v[186:187]
	v_pk_add_f32 v[122:123], v[122:123], v[188:189]
	v_pk_add_f32 v[124:125], v[124:125], v[190:191]
	global_store_dwordx4 v219, v[126:129], s[16:17]
	global_store_dwordx4 v226, v[122:125], s[16:17]
	v_cvt_pk_bf16_f32 v248, v126, v127
	v_cvt_pk_bf16_f32 v249, v128, v129
	v_cvt_pk_bf16_f32 v250, v122, v123
	v_cvt_pk_bf16_f32 v251, v124, v125
	v_mul_f32_e32 v229, v126, v126
	v_mul_f32_e32 v230, v122, v122
	v_fmac_f32_e32 v229, v127, v127
	v_fmac_f32_e32 v230, v123, v123
	v_fmac_f32_e32 v229, v128, v128
	v_fmac_f32_e32 v230, v124, v124
	v_fmac_f32_e32 v229, v129, v129
	v_fmac_f32_e32 v230, v125, v125
	global_store_dwordx2 v218, v[248:249], s[64:65]
	global_store_dwordx2 v228, v[250:251], s[64:65]
	ds_write_b128 v221, v[118:121]
	ds_write_b128 v221, v[114:117] offset:16
	ds_read_b128 v[118:121], v222
	ds_read_b128 v[114:117], v222 offset:1152
	s_waitcnt lgkmcnt(0)
	v_pk_add_f32 v[118:119], v[118:119], v[192:193]
	v_pk_add_f32 v[120:121], v[120:121], v[194:195]
	v_pk_add_f32 v[114:115], v[114:115], v[196:197]
	v_pk_add_f32 v[116:117], v[116:117], v[198:199]
	global_store_dwordx4 v219, v[118:121], s[16:17] offset:512
	global_store_dwordx4 v226, v[114:117], s[16:17] offset:512
	v_cvt_pk_bf16_f32 v248, v118, v119
	v_cvt_pk_bf16_f32 v249, v120, v121
	v_cvt_pk_bf16_f32 v250, v114, v115
	v_cvt_pk_bf16_f32 v251, v116, v117
	v_fmac_f32_e32 v229, v118, v118
	v_fmac_f32_e32 v230, v114, v114
	v_fmac_f32_e32 v229, v119, v119
	v_fmac_f32_e32 v230, v115, v115
	v_fmac_f32_e32 v229, v120, v120
	v_fmac_f32_e32 v230, v116, v116
	v_fmac_f32_e32 v229, v121, v121
	v_fmac_f32_e32 v230, v117, v117
	global_store_dwordx2 v218, v[248:249], s[64:65] offset:256
	global_store_dwordx2 v228, v[250:251], s[64:65] offset:256
	s_nop 1
	v_add_f32_dpp v229, v229, v229 quad_perm:[1,0,3,2] row_mask:0xf bank_mask:0xf
	v_add_f32_dpp v230, v230, v230 quad_perm:[1,0,3,2] row_mask:0xf bank_mask:0xf
	s_nop 0
	v_add_f32_dpp v229, v229, v229 quad_perm:[2,3,0,1] row_mask:0xf bank_mask:0xf
	v_add_f32_dpp v230, v230, v230 quad_perm:[2,3,0,1] row_mask:0xf bank_mask:0xf
	s_nop 0
	v_add_f32_dpp v229, v229, v229 row_half_mirror row_mask:0xf bank_mask:0xf
	v_add_f32_dpp v230, v230, v230 row_half_mirror row_mask:0xf bank_mask:0xf
	s_nop 0
	s_mov_b32 exec_lo, 0x1010101
	s_mov_b32 exec_hi, 0x1010101
	global_atomic_add_f32 v217, v229, s[10:11]
	global_atomic_add_f32 v217, v230, s[10:11] offset:32
	s_mov_b64 exec, -1
	v_add_u32_e32 v223, 0x20000, v220
	v_add_u32_e32 v224, 0x8000, v223
	global_load_dwordx4 v[184:187], v223, s[98:99]
	global_load_dwordx4 v[188:191], v224, s[98:99]
	global_load_dwordx4 v[192:195], v223, s[98:99] offset:512
	global_load_dwordx4 v[196:199], v224, s[98:99] offset:512
	s_waitcnt vmcnt(14)
	v_add_u32_e32 v225, 0x10000, v219
	v_add_u32_e32 v227, 0x8000, v218
	v_add_u32_e32 v226, 0x8000, v225
	v_add_u32_e32 v228, 0x4000, v227
	ds_write_b128 v221, v[110:113]
	ds_write_b128 v221, v[106:109] offset:16
	ds_read_b128 v[110:113], v222
	ds_read_b128 v[106:109], v222 offset:1152
	s_waitcnt lgkmcnt(0)
	v_pk_add_f32 v[110:111], v[110:111], v[200:201]
	v_pk_add_f32 v[112:113], v[112:113], v[202:203]
	v_pk_add_f32 v[106:107], v[106:107], v[204:205]
	v_pk_add_f32 v[108:109], v[108:109], v[206:207]
	global_store_dwordx4 v225, v[110:113], s[16:17]
	global_store_dwordx4 v226, v[106:109], s[16:17]
	v_cvt_pk_bf16_f32 v248, v110, v111
	v_cvt_pk_bf16_f32 v249, v112, v113
	v_cvt_pk_bf16_f32 v250, v106, v107
	v_cvt_pk_bf16_f32 v251, v108, v109
	v_mul_f32_e32 v229, v110, v110
	v_mul_f32_e32 v230, v106, v106
	v_fmac_f32_e32 v229, v111, v111
	v_fmac_f32_e32 v230, v107, v107
	v_fmac_f32_e32 v229, v112, v112
	v_fmac_f32_e32 v230, v108, v108
	v_fmac_f32_e32 v229, v113, v113
	v_fmac_f32_e32 v230, v109, v109
	global_store_dwordx2 v227, v[248:249], s[64:65]
	global_store_dwordx2 v228, v[250:251], s[64:65]
	ds_write_b128 v221, v[102:105]
	ds_write_b128 v221, v[98:101] offset:16
	ds_read_b128 v[102:105], v222
	ds_read_b128 v[98:101], v222 offset:1152
	s_waitcnt lgkmcnt(0)
; __device__ __forceinline__ unsigned pk(float lo, float hi) { return pg8::cvt_pk_bf16(lo, hi); }
; __device__ __forceinline__ float dot4(f32x4 v) { return (v[0] * v[0] + v[1] * v[1]) + (v[2] * v[2] + v[3] * v[3]); }
;     __device__ __forceinline__ void operator()(const pg8::f32x4 (&acc)[2][2][4][2], const pg8::Unit& u, int wr, int wc, int fr, int fq) const {
;         const int row0 = u.pm * 256 + wr * 64 + fr;
; #pragma unroll
;         for (int ai = 0; ai < 2; ++ai)
; #pragma unroll
;             for (int m = 0; m < 4; ++m) {
;                 const int row = row0 + ai * 128 + m * 16;
;                 const float* xi = (row < MP) ? xin_p + (size_t)row * DM : xin_s + (size_t)(row - MP) * DM;
;                 float sq = 0.f;
; #pragma unroll
;                 for (int bj = 0; bj < 2; ++bj) { const int col = u.pn * 256 + bj * 128 + wc * 32 + 8 * fq;
;                     const f32x4 a0 = *(const f32x4*)(xi + col) + acc[ai][bj][m][0], a1 = *(const f32x4*)(xi + col + 4) + acc[ai][bj][m][1];
;                     *(f32x4*)(xout + (size_t)row * DM + col) = a0; *(f32x4*)(xout + (size_t)row * DM + col + 4) = a1;
;                     u32x4 w; w.x = pk(a0[0], a0[1]); w.y = pk(a0[2], a0[3]); w.z = pk(a1[0], a1[1]); w.w = pk(a1[2], a1[3]);
;                     *(u32x4*)(xb + (size_t)row * DM + col) = w;
;                     sq += dot4(a0) + dot4(a1); }
;                 sq += __shfl_xor(sq, 16); sq += __shfl_xor(sq, 32);
;                 if (fq == 0) atomicAdd(ssout + row, sq);
;             }
;     }
	v_pk_add_f32 v[102:103], v[102:103], v[208:209]
	v_pk_add_f32 v[104:105], v[104:105], v[210:211]
	v_pk_add_f32 v[98:99], v[98:99], v[212:213]
	v_pk_add_f32 v[100:101], v[100:101], v[214:215]
	global_store_dwordx4 v225, v[102:105], s[16:17] offset:512
	global_store_dwordx4 v226, v[98:101], s[16:17] offset:512
	v_cvt_pk_bf16_f32 v248, v102, v103
	v_cvt_pk_bf16_f32 v249, v104, v105
	v_cvt_pk_bf16_f32 v250, v98, v99
	v_cvt_pk_bf16_f32 v251, v100, v101
	v_fmac_f32_e32 v229, v102, v102
	v_fmac_f32_e32 v230, v98, v98
	v_fmac_f32_e32 v229, v103, v103
	v_fmac_f32_e32 v230, v99, v99
	v_fmac_f32_e32 v229, v104, v104
	v_fmac_f32_e32 v230, v100, v100
	v_fmac_f32_e32 v229, v105, v105
	v_fmac_f32_e32 v230, v101, v101
	global_store_dwordx2 v227, v[248:249], s[64:65] offset:256
	global_store_dwordx2 v228, v[250:251], s[64:65] offset:256
	s_nop 1
	v_add_f32_dpp v229, v229, v229 quad_perm:[1,0,3,2] row_mask:0xf bank_mask:0xf
	v_add_f32_dpp v230, v230, v230 quad_perm:[1,0,3,2] row_mask:0xf bank_mask:0xf
	s_nop 0
	v_add_f32_dpp v229, v229, v229 quad_perm:[2,3,0,1] row_mask:0xf bank_mask:0xf
	v_add_f32_dpp v230, v230, v230 quad_perm:[2,3,0,1] row_mask:0xf bank_mask:0xf
	s_nop 0
	v_add_f32_dpp v229, v229, v229 row_half_mirror row_mask:0xf bank_mask:0xf
	v_add_f32_dpp v230, v230, v230 row_half_mirror row_mask:0xf bank_mask:0xf
	s_nop 0
	s_mov_b32 exec_lo, 0x1010101
	s_mov_b32 exec_hi, 0x1010101
	global_atomic_add_f32 v217, v229, s[10:11] offset:64
	global_atomic_add_f32 v217, v230, s[10:11] offset:96
	s_mov_b64 exec, -1
	v_add_u32_e32 v223, 0x30000, v220
	v_add_u32_e32 v224, 0x8000, v223
	global_load_dwordx4 v[200:203], v223, s[98:99]
	global_load_dwordx4 v[204:207], v224, s[98:99]
	global_load_dwordx4 v[208:211], v223, s[98:99] offset:512
	global_load_dwordx4 v[212:215], v224, s[98:99] offset:512
	s_waitcnt vmcnt(14)
	v_add_u32_e32 v225, 0x20000, v219
	v_add_u32_e32 v227, 0x10000, v218
	v_add_u32_e32 v226, 0x8000, v225
	v_add_u32_e32 v228, 0x4000, v227
	ds_write_b128 v221, v[94:97]
	ds_write_b128 v221, v[90:93] offset:16
	ds_read_b128 v[94:97], v222
	ds_read_b128 v[90:93], v222 offset:1152
	s_waitcnt lgkmcnt(0)
	v_pk_add_f32 v[94:95], v[94:95], v[184:185]
	v_pk_add_f32 v[96:97], v[96:97], v[186:187]
	v_pk_add_f32 v[90:91], v[90:91], v[188:189]
	v_pk_add_f32 v[92:93], v[92:93], v[190:191]
	global_store_dwordx4 v225, v[94:97], s[16:17]
	global_store_dwordx4 v226, v[90:93], s[16:17]
	v_cvt_pk_bf16_f32 v248, v94, v95
	v_cvt_pk_bf16_f32 v249, v96, v97
	v_cvt_pk_bf16_f32 v250, v90, v91
	v_cvt_pk_bf16_f32 v251, v92, v93
	v_mul_f32_e32 v229, v94, v94
	v_mul_f32_e32 v230, v90, v90
	v_fmac_f32_e32 v229, v95, v95
	v_fmac_f32_e32 v230, v91, v91
	v_fmac_f32_e32 v229, v96, v96
	v_fmac_f32_e32 v230, v92, v92
	v_fmac_f32_e32 v229, v97, v97
	v_fmac_f32_e32 v230, v93, v93
	global_store_dwordx2 v227, v[248:249], s[64:65]
	global_store_dwordx2 v228, v[250:251], s[64:65]
	ds_write_b128 v221, v[86:89]
	ds_write_b128 v221, v[82:85] offset:16
	ds_read_b128 v[86:89], v222
	ds_read_b128 v[82:85], v222 offset:1152
	s_waitcnt lgkmcnt(0)
	v_pk_add_f32 v[86:87], v[86:87], v[192:193]
	v_pk_add_f32 v[88:89], v[88:89], v[194:195]
	v_pk_add_f32 v[82:83], v[82:83], v[196:197]
	v_pk_add_f32 v[84:85], v[84:85], v[198:199]
	global_store_dwordx4 v225, v[86:89], s[16:17] offset:512
	global_store_dwordx4 v226, v[82:85], s[16:17] offset:512
	v_cvt_pk_bf16_f32 v248, v86, v87
	v_cvt_pk_bf16_f32 v249, v88, v89
	v_cvt_pk_bf16_f32 v250, v82, v83
	v_cvt_pk_bf16_f32 v251, v84, v85
	v_fmac_f32_e32 v229, v86, v86
	v_fmac_f32_e32 v230, v82, v82
	v_fmac_f32_e32 v229, v87, v87
	v_fmac_f32_e32 v230, v83, v83
	v_fmac_f32_e32 v229, v88, v88
	v_fmac_f32_e32 v230, v84, v84
	v_fmac_f32_e32 v229, v89, v89
	v_fmac_f32_e32 v230, v85, v85
	global_store_dwordx2 v227, v[248:249], s[64:65] offset:256
	global_store_dwordx2 v228, v[250:251], s[64:65] offset:256
	s_nop 1
	v_add_f32_dpp v229, v229, v229 quad_perm:[1,0,3,2] row_mask:0xf bank_mask:0xf
	v_add_f32_dpp v230, v230, v230 quad_perm:[1,0,3,2] row_mask:0xf bank_mask:0xf
	s_nop 0
	v_add_f32_dpp v229, v229, v229 quad_perm:[2,3,0,1] row_mask:0xf bank_mask:0xf
	v_add_f32_dpp v230, v230, v230 quad_perm:[2,3,0,1] row_mask:0xf bank_mask:0xf
	s_nop 0
	v_add_f32_dpp v229, v229, v229 row_half_mirror row_mask:0xf bank_mask:0xf
	v_add_f32_dpp v230, v230, v230 row_half_mirror row_mask:0xf bank_mask:0xf
	s_nop 0
	s_mov_b32 exec_lo, 0x1010101
	s_mov_b32 exec_hi, 0x1010101
	global_atomic_add_f32 v217, v229, s[10:11] offset:128
	global_atomic_add_f32 v217, v230, s[10:11] offset:160
	s_mov_b64 exec, -1
	v_add_u32_e32 v223, 0x80000, v220
	v_add_u32_e32 v224, 0x8000, v223
	global_load_dwordx4 v[184:187], v223, s[98:99]
	global_load_dwordx4 v[188:191], v224, s[98:99]
	global_load_dwordx4 v[192:195], v223, s[98:99] offset:512
	global_load_dwordx4 v[196:199], v224, s[98:99] offset:512
	s_waitcnt vmcnt(14)
	v_add_u32_e32 v225, 0x30000, v219
	v_add_u32_e32 v227, 0x18000, v218
	v_add_u32_e32 v226, 0x8000, v225
	v_add_u32_e32 v228, 0x4000, v227
	ds_write_b128 v221, v[78:81]
	ds_write_b128 v221, v[74:77] offset:16
	ds_read_b128 v[78:81], v222
	ds_read_b128 v[74:77], v222 offset:1152
	s_waitcnt lgkmcnt(0)
	v_pk_add_f32 v[78:79], v[78:79], v[200:201]
	v_pk_add_f32 v[80:81], v[80:81], v[202:203]
	v_pk_add_f32 v[74:75], v[74:75], v[204:205]
	v_pk_add_f32 v[76:77], v[76:77], v[206:207]
	global_store_dwordx4 v225, v[78:81], s[16:17]
	global_store_dwordx4 v226, v[74:77], s[16:17]
	v_cvt_pk_bf16_f32 v248, v78, v79
	v_cvt_pk_bf16_f32 v249, v80, v81
	v_cvt_pk_bf16_f32 v250, v74, v75
	v_cvt_pk_bf16_f32 v251, v76, v77
	v_mul_f32_e32 v229, v78, v78
	v_mul_f32_e32 v230, v74, v74
	v_fmac_f32_e32 v229, v79, v79
	v_fmac_f32_e32 v230, v75, v75
	v_fmac_f32_e32 v229, v80, v80
	v_fmac_f32_e32 v230, v76, v76
	v_fmac_f32_e32 v229, v81, v81
	v_fmac_f32_e32 v230, v77, v77
	global_store_dwordx2 v227, v[248:249], s[64:65]
	global_store_dwordx2 v228, v[250:251], s[64:65]
	ds_write_b128 v221, v[70:73]
	ds_write_b128 v221, v[66:69] offset:16
	ds_read_b128 v[70:73], v222
	ds_read_b128 v[66:69], v222 offset:1152
	s_waitcnt lgkmcnt(0)
; __device__ __forceinline__ unsigned pk(float lo, float hi) { return pg8::cvt_pk_bf16(lo, hi); }
; __device__ __forceinline__ float dot4(f32x4 v) { return (v[0] * v[0] + v[1] * v[1]) + (v[2] * v[2] + v[3] * v[3]); }
;     __device__ __forceinline__ void operator()(const pg8::f32x4 (&acc)[2][2][4][2], const pg8::Unit& u, int wr, int wc, int fr, int fq) const {
;         const int row0 = u.pm * 256 + wr * 64 + fr;
; #pragma unroll
;         for (int ai = 0; ai < 2; ++ai)
; #pragma unroll
;             for (int m = 0; m < 4; ++m) {
;                 const int row = row0 + ai * 128 + m * 16;
;                 const float* xi = (row < MP) ? xin_p + (size_t)row * DM : xin_s + (size_t)(row - MP) * DM;
;                 float sq = 0.f;
; #pragma unroll
;                 for (int bj = 0; bj < 2; ++bj) { const int col = u.pn * 256 + bj * 128 + wc * 32 + 8 * fq;
;                     const f32x4 a0 = *(const f32x4*)(xi + col) + acc[ai][bj][m][0], a1 = *(const f32x4*)(xi + col + 4) + acc[ai][bj][m][1];
;                     *(f32x4*)(xout + (size_t)row * DM + col) = a0; *(f32x4*)(xout + (size_t)row * DM + col + 4) = a1;
;                     u32x4 w; w.x = pk(a0[0], a0[1]); w.y = pk(a0[2], a0[3]); w.z = pk(a1[0], a1[1]); w.w = pk(a1[2], a1[3]);
;                     *(u32x4*)(xb + (size_t)row * DM + col) = w;
;                     sq += dot4(a0) + dot4(a1); }
;                 sq += __shfl_xor(sq, 16); sq += __shfl_xor(sq, 32);
;                 if (fq == 0) atomicAdd(ssout + row, sq);
;             }
;     }
	v_pk_add_f32 v[70:71], v[70:71], v[208:209]
	v_pk_add_f32 v[72:73], v[72:73], v[210:211]
	v_pk_add_f32 v[66:67], v[66:67], v[212:213]
	v_pk_add_f32 v[68:69], v[68:69], v[214:215]
	global_store_dwordx4 v225, v[70:73], s[16:17] offset:512
	global_store_dwordx4 v226, v[66:69], s[16:17] offset:512
	v_cvt_pk_bf16_f32 v248, v70, v71
	v_cvt_pk_bf16_f32 v249, v72, v73
	v_cvt_pk_bf16_f32 v250, v66, v67
	v_cvt_pk_bf16_f32 v251, v68, v69
	v_fmac_f32_e32 v229, v70, v70
	v_fmac_f32_e32 v230, v66, v66
	v_fmac_f32_e32 v229, v71, v71
	v_fmac_f32_e32 v230, v67, v67
	v_fmac_f32_e32 v229, v72, v72
	v_fmac_f32_e32 v230, v68, v68
	v_fmac_f32_e32 v229, v73, v73
	v_fmac_f32_e32 v230, v69, v69
	global_store_dwordx2 v227, v[248:249], s[64:65] offset:256
	global_store_dwordx2 v228, v[250:251], s[64:65] offset:256
	s_nop 1
	v_add_f32_dpp v229, v229, v229 quad_perm:[1,0,3,2] row_mask:0xf bank_mask:0xf
	v_add_f32_dpp v230, v230, v230 quad_perm:[1,0,3,2] row_mask:0xf bank_mask:0xf
	s_nop 0
	v_add_f32_dpp v229, v229, v229 quad_perm:[2,3,0,1] row_mask:0xf bank_mask:0xf
	v_add_f32_dpp v230, v230, v230 quad_perm:[2,3,0,1] row_mask:0xf bank_mask:0xf
	s_nop 0
	v_add_f32_dpp v229, v229, v229 row_half_mirror row_mask:0xf bank_mask:0xf
	v_add_f32_dpp v230, v230, v230 row_half_mirror row_mask:0xf bank_mask:0xf
	s_nop 0
	s_mov_b32 exec_lo, 0x1010101
	s_mov_b32 exec_hi, 0x1010101
	global_atomic_add_f32 v217, v229, s[10:11] offset:192
	global_atomic_add_f32 v217, v230, s[10:11] offset:224
	s_mov_b64 exec, -1
	v_add_u32_e32 v223, 0x90000, v220
	v_add_u32_e32 v224, 0x8000, v223
	global_load_dwordx4 v[200:203], v223, s[98:99]
	global_load_dwordx4 v[204:207], v224, s[98:99]
	global_load_dwordx4 v[208:211], v223, s[98:99] offset:512
	global_load_dwordx4 v[212:215], v224, s[98:99] offset:512
	s_waitcnt vmcnt(14)
	v_add_u32_e32 v225, 0x80000, v219
	v_add_u32_e32 v227, 0x40000, v218
	v_add_u32_e32 v226, 0x8000, v225
	v_add_u32_e32 v228, 0x4000, v227
	ds_write_b128 v221, v[62:65]
	ds_write_b128 v221, v[58:61] offset:16
	ds_read_b128 v[62:65], v222
	ds_read_b128 v[58:61], v222 offset:1152
	s_waitcnt lgkmcnt(0)
	v_pk_add_f32 v[62:63], v[62:63], v[184:185]
	v_pk_add_f32 v[64:65], v[64:65], v[186:187]
	v_pk_add_f32 v[58:59], v[58:59], v[188:189]
	v_pk_add_f32 v[60:61], v[60:61], v[190:191]
	global_store_dwordx4 v225, v[62:65], s[16:17]
	global_store_dwordx4 v226, v[58:61], s[16:17]
	v_cvt_pk_bf16_f32 v248, v62, v63
	v_cvt_pk_bf16_f32 v249, v64, v65
	v_cvt_pk_bf16_f32 v250, v58, v59
	v_cvt_pk_bf16_f32 v251, v60, v61
	v_mul_f32_e32 v229, v62, v62
	v_mul_f32_e32 v230, v58, v58
	v_fmac_f32_e32 v229, v63, v63
	v_fmac_f32_e32 v230, v59, v59
	v_fmac_f32_e32 v229, v64, v64
	v_fmac_f32_e32 v230, v60, v60
	v_fmac_f32_e32 v229, v65, v65
	v_fmac_f32_e32 v230, v61, v61
	global_store_dwordx2 v227, v[248:249], s[64:65]
	global_store_dwordx2 v228, v[250:251], s[64:65]
	ds_write_b128 v221, v[54:57]
	ds_write_b128 v221, v[50:53] offset:16
	ds_read_b128 v[54:57], v222
	ds_read_b128 v[50:53], v222 offset:1152
	s_waitcnt lgkmcnt(0)
	v_pk_add_f32 v[54:55], v[54:55], v[192:193]
	v_pk_add_f32 v[56:57], v[56:57], v[194:195]
	v_pk_add_f32 v[50:51], v[50:51], v[196:197]
	v_pk_add_f32 v[52:53], v[52:53], v[198:199]
	global_store_dwordx4 v225, v[54:57], s[16:17] offset:512
	global_store_dwordx4 v226, v[50:53], s[16:17] offset:512
	v_cvt_pk_bf16_f32 v248, v54, v55
	v_cvt_pk_bf16_f32 v249, v56, v57
	v_cvt_pk_bf16_f32 v250, v50, v51
	v_cvt_pk_bf16_f32 v251, v52, v53
	v_fmac_f32_e32 v229, v54, v54
	v_fmac_f32_e32 v230, v50, v50
	v_fmac_f32_e32 v229, v55, v55
	v_fmac_f32_e32 v230, v51, v51
	v_fmac_f32_e32 v229, v56, v56
	v_fmac_f32_e32 v230, v52, v52
	v_fmac_f32_e32 v229, v57, v57
	v_fmac_f32_e32 v230, v53, v53
	global_store_dwordx2 v227, v[248:249], s[64:65] offset:256
	global_store_dwordx2 v228, v[250:251], s[64:65] offset:256
	s_nop 1
	v_add_f32_dpp v229, v229, v229 quad_perm:[1,0,3,2] row_mask:0xf bank_mask:0xf
	v_add_f32_dpp v230, v230, v230 quad_perm:[1,0,3,2] row_mask:0xf bank_mask:0xf
	s_nop 0
	v_add_f32_dpp v229, v229, v229 quad_perm:[2,3,0,1] row_mask:0xf bank_mask:0xf
	v_add_f32_dpp v230, v230, v230 quad_perm:[2,3,0,1] row_mask:0xf bank_mask:0xf
	s_nop 0
	v_add_f32_dpp v229, v229, v229 row_half_mirror row_mask:0xf bank_mask:0xf
	v_add_f32_dpp v230, v230, v230 row_half_mirror row_mask:0xf bank_mask:0xf
	s_nop 0
	s_mov_b32 exec_lo, 0x1010101
	s_mov_b32 exec_hi, 0x1010101
	global_atomic_add_f32 v217, v229, s[10:11] offset:512
	global_atomic_add_f32 v217, v230, s[10:11] offset:544
	s_mov_b64 exec, -1
	v_add_u32_e32 v223, 0xa0000, v220
	v_add_u32_e32 v224, 0x8000, v223
	global_load_dwordx4 v[184:187], v223, s[98:99]
	global_load_dwordx4 v[188:191], v224, s[98:99]
	global_load_dwordx4 v[192:195], v223, s[98:99] offset:512
	global_load_dwordx4 v[196:199], v224, s[98:99] offset:512
	s_waitcnt vmcnt(14)
	v_add_u32_e32 v225, 0x90000, v219
	v_add_u32_e32 v227, 0x48000, v218
	v_add_u32_e32 v226, 0x8000, v225
	v_add_u32_e32 v228, 0x4000, v227
	ds_write_b128 v221, v[46:49]
	ds_write_b128 v221, v[42:45] offset:16
	ds_read_b128 v[46:49], v222
	ds_read_b128 v[42:45], v222 offset:1152
	s_waitcnt lgkmcnt(0)
	v_pk_add_f32 v[46:47], v[46:47], v[200:201]
	v_pk_add_f32 v[48:49], v[48:49], v[202:203]
	v_pk_add_f32 v[42:43], v[42:43], v[204:205]
	v_pk_add_f32 v[44:45], v[44:45], v[206:207]
	global_store_dwordx4 v225, v[46:49], s[16:17]
	global_store_dwordx4 v226, v[42:45], s[16:17]
	v_cvt_pk_bf16_f32 v248, v46, v47
	v_cvt_pk_bf16_f32 v249, v48, v49
	v_cvt_pk_bf16_f32 v250, v42, v43
	v_cvt_pk_bf16_f32 v251, v44, v45
	v_mul_f32_e32 v229, v46, v46
	v_mul_f32_e32 v230, v42, v42
	v_fmac_f32_e32 v229, v47, v47
	v_fmac_f32_e32 v230, v43, v43
	v_fmac_f32_e32 v229, v48, v48
	v_fmac_f32_e32 v230, v44, v44
	v_fmac_f32_e32 v229, v49, v49
	v_fmac_f32_e32 v230, v45, v45
	global_store_dwordx2 v227, v[248:249], s[64:65]
	global_store_dwordx2 v228, v[250:251], s[64:65]
	ds_write_b128 v221, v[38:41]
	ds_write_b128 v221, v[34:37] offset:16
	ds_read_b128 v[38:41], v222
	ds_read_b128 v[34:37], v222 offset:1152
	s_waitcnt lgkmcnt(0)
; __device__ __forceinline__ unsigned pk(float lo, float hi) { return pg8::cvt_pk_bf16(lo, hi); }
; __device__ __forceinline__ float dot4(f32x4 v) { return (v[0] * v[0] + v[1] * v[1]) + (v[2] * v[2] + v[3] * v[3]); }
;     __device__ __forceinline__ void operator()(const pg8::f32x4 (&acc)[2][2][4][2], const pg8::Unit& u, int wr, int wc, int fr, int fq) const {
;         const int row0 = u.pm * 256 + wr * 64 + fr;
; #pragma unroll
;         for (int ai = 0; ai < 2; ++ai)
; #pragma unroll
;             for (int m = 0; m < 4; ++m) {
;                 const int row = row0 + ai * 128 + m * 16;
;                 const float* xi = (row < MP) ? xin_p + (size_t)row * DM : xin_s + (size_t)(row - MP) * DM;
;                 float sq = 0.f;
; #pragma unroll
;                 for (int bj = 0; bj < 2; ++bj) { const int col = u.pn * 256 + bj * 128 + wc * 32 + 8 * fq;
;                     const f32x4 a0 = *(const f32x4*)(xi + col) + acc[ai][bj][m][0], a1 = *(const f32x4*)(xi + col + 4) + acc[ai][bj][m][1];
;                     *(f32x4*)(xout + (size_t)row * DM + col) = a0; *(f32x4*)(xout + (size_t)row * DM + col + 4) = a1;
;                     u32x4 w; w.x = pk(a0[0], a0[1]); w.y = pk(a0[2], a0[3]); w.z = pk(a1[0], a1[1]); w.w = pk(a1[2], a1[3]);
;                     *(u32x4*)(xb + (size_t)row * DM + col) = w;
;                     sq += dot4(a0) + dot4(a1); }
;                 sq += __shfl_xor(sq, 16); sq += __shfl_xor(sq, 32);
;                 if (fq == 0) atomicAdd(ssout + row, sq);
;             }
;     }
	v_pk_add_f32 v[38:39], v[38:39], v[208:209]
	v_pk_add_f32 v[40:41], v[40:41], v[210:211]
	v_pk_add_f32 v[34:35], v[34:35], v[212:213]
	v_pk_add_f32 v[36:37], v[36:37], v[214:215]
	global_store_dwordx4 v225, v[38:41], s[16:17] offset:512
	global_store_dwordx4 v226, v[34:37], s[16:17] offset:512
	v_cvt_pk_bf16_f32 v248, v38, v39
	v_cvt_pk_bf16_f32 v249, v40, v41
	v_cvt_pk_bf16_f32 v250, v34, v35
	v_cvt_pk_bf16_f32 v251, v36, v37
	v_fmac_f32_e32 v229, v38, v38
	v_fmac_f32_e32 v230, v34, v34
	v_fmac_f32_e32 v229, v39, v39
	v_fmac_f32_e32 v230, v35, v35
	v_fmac_f32_e32 v229, v40, v40
	v_fmac_f32_e32 v230, v36, v36
	v_fmac_f32_e32 v229, v41, v41
	v_fmac_f32_e32 v230, v37, v37
	global_store_dwordx2 v227, v[248:249], s[64:65] offset:256
	global_store_dwordx2 v228, v[250:251], s[64:65] offset:256
	s_nop 1
	v_add_f32_dpp v229, v229, v229 quad_perm:[1,0,3,2] row_mask:0xf bank_mask:0xf
	v_add_f32_dpp v230, v230, v230 quad_perm:[1,0,3,2] row_mask:0xf bank_mask:0xf
	s_nop 0
	v_add_f32_dpp v229, v229, v229 quad_perm:[2,3,0,1] row_mask:0xf bank_mask:0xf
	v_add_f32_dpp v230, v230, v230 quad_perm:[2,3,0,1] row_mask:0xf bank_mask:0xf
	s_nop 0
	v_add_f32_dpp v229, v229, v229 row_half_mirror row_mask:0xf bank_mask:0xf
	v_add_f32_dpp v230, v230, v230 row_half_mirror row_mask:0xf bank_mask:0xf
	s_nop 0
	s_mov_b32 exec_lo, 0x1010101
	s_mov_b32 exec_hi, 0x1010101
	global_atomic_add_f32 v217, v229, s[10:11] offset:576
	global_atomic_add_f32 v217, v230, s[10:11] offset:608
	s_mov_b64 exec, -1
	v_add_u32_e32 v223, 0xb0000, v220
	v_add_u32_e32 v224, 0x8000, v223
	global_load_dwordx4 v[200:203], v223, s[98:99]
	global_load_dwordx4 v[204:207], v224, s[98:99]
	global_load_dwordx4 v[208:211], v223, s[98:99] offset:512
	global_load_dwordx4 v[212:215], v224, s[98:99] offset:512
	s_waitcnt vmcnt(14)
	v_add_u32_e32 v225, 0xa0000, v219
	v_add_u32_e32 v227, 0x50000, v218
	v_add_u32_e32 v226, 0x8000, v225
	v_add_u32_e32 v228, 0x4000, v227
	ds_write_b128 v221, v[30:33]
	ds_write_b128 v221, v[26:29] offset:16
	ds_read_b128 v[30:33], v222
	ds_read_b128 v[26:29], v222 offset:1152
	s_waitcnt lgkmcnt(0)
	v_pk_add_f32 v[30:31], v[30:31], v[184:185]
	v_pk_add_f32 v[32:33], v[32:33], v[186:187]
	v_pk_add_f32 v[26:27], v[26:27], v[188:189]
	v_pk_add_f32 v[28:29], v[28:29], v[190:191]
	global_store_dwordx4 v225, v[30:33], s[16:17]
	global_store_dwordx4 v226, v[26:29], s[16:17]
	v_cvt_pk_bf16_f32 v248, v30, v31
	v_cvt_pk_bf16_f32 v249, v32, v33
	v_cvt_pk_bf16_f32 v250, v26, v27
	v_cvt_pk_bf16_f32 v251, v28, v29
	v_mul_f32_e32 v229, v30, v30
	v_mul_f32_e32 v230, v26, v26
	v_fmac_f32_e32 v229, v31, v31
	v_fmac_f32_e32 v230, v27, v27
	v_fmac_f32_e32 v229, v32, v32
	v_fmac_f32_e32 v230, v28, v28
	v_fmac_f32_e32 v229, v33, v33
	v_fmac_f32_e32 v230, v29, v29
	global_store_dwordx2 v227, v[248:249], s[64:65]
	global_store_dwordx2 v228, v[250:251], s[64:65]
	ds_write_b128 v221, v[22:25]
	ds_write_b128 v221, v[18:21] offset:16
	ds_read_b128 v[22:25], v222
	ds_read_b128 v[18:21], v222 offset:1152
	s_waitcnt lgkmcnt(0)
; __device__ __forceinline__ unsigned pk(float lo, float hi) { return pg8::cvt_pk_bf16(lo, hi); }
; __device__ __forceinline__ float dot4(f32x4 v) { return (v[0] * v[0] + v[1] * v[1]) + (v[2] * v[2] + v[3] * v[3]); }
;     __device__ __forceinline__ void operator()(const pg8::f32x4 (&acc)[2][2][4][2], const pg8::Unit& u, int wr, int wc, int fr, int fq) const {
;         const int row0 = u.pm * 256 + wr * 64 + fr;
; #pragma unroll
;         for (int ai = 0; ai < 2; ++ai)
; #pragma unroll
;             for (int m = 0; m < 4; ++m) {
;                 const int row = row0 + ai * 128 + m * 16;
;                 const float* xi = (row < MP) ? xin_p + (size_t)row * DM : xin_s + (size_t)(row - MP) * DM;
;                 float sq = 0.f;
; #pragma unroll
;                 for (int bj = 0; bj < 2; ++bj) { const int col = u.pn * 256 + bj * 128 + wc * 32 + 8 * fq;
;                     const f32x4 a0 = *(const f32x4*)(xi + col) + acc[ai][bj][m][0], a1 = *(const f32x4*)(xi + col + 4) + acc[ai][bj][m][1];
;                     *(f32x4*)(xout + (size_t)row * DM + col) = a0; *(f32x4*)(xout + (size_t)row * DM + col + 4) = a1;
;                     u32x4 w; w.x = pk(a0[0], a0[1]); w.y = pk(a0[2], a0[3]); w.z = pk(a1[0], a1[1]); w.w = pk(a1[2], a1[3]);
;                     *(u32x4*)(xb + (size_t)row * DM + col) = w;
;                     sq += dot4(a0) + dot4(a1); }
;                 sq += __shfl_xor(sq, 16); sq += __shfl_xor(sq, 32);
;                 if (fq == 0) atomicAdd(ssout + row, sq);
;             }
;     }
	v_pk_add_f32 v[22:23], v[22:23], v[192:193]
	v_pk_add_f32 v[24:25], v[24:25], v[194:195]
	v_pk_add_f32 v[18:19], v[18:19], v[196:197]
	v_pk_add_f32 v[20:21], v[20:21], v[198:199]
	global_store_dwordx4 v225, v[22:25], s[16:17] offset:512
	global_store_dwordx4 v226, v[18:21], s[16:17] offset:512
	v_cvt_pk_bf16_f32 v248, v22, v23
	v_cvt_pk_bf16_f32 v249, v24, v25
	v_cvt_pk_bf16_f32 v250, v18, v19
	v_cvt_pk_bf16_f32 v251, v20, v21
	v_fmac_f32_e32 v229, v22, v22
	v_fmac_f32_e32 v230, v18, v18
	v_fmac_f32_e32 v229, v23, v23
	v_fmac_f32_e32 v230, v19, v19
	v_fmac_f32_e32 v229, v24, v24
	v_fmac_f32_e32 v230, v20, v20
	v_fmac_f32_e32 v229, v25, v25
	v_fmac_f32_e32 v230, v21, v21
	global_store_dwordx2 v227, v[248:249], s[64:65] offset:256
	global_store_dwordx2 v228, v[250:251], s[64:65] offset:256
	s_nop 1
	v_add_f32_dpp v229, v229, v229 quad_perm:[1,0,3,2] row_mask:0xf bank_mask:0xf
	v_add_f32_dpp v230, v230, v230 quad_perm:[1,0,3,2] row_mask:0xf bank_mask:0xf
	s_nop 0
	v_add_f32_dpp v229, v229, v229 quad_perm:[2,3,0,1] row_mask:0xf bank_mask:0xf
	v_add_f32_dpp v230, v230, v230 quad_perm:[2,3,0,1] row_mask:0xf bank_mask:0xf
	s_nop 0
	v_add_f32_dpp v229, v229, v229 row_half_mirror row_mask:0xf bank_mask:0xf
	v_add_f32_dpp v230, v230, v230 row_half_mirror row_mask:0xf bank_mask:0xf
	s_nop 0
	s_mov_b32 exec_lo, 0x1010101
	s_mov_b32 exec_hi, 0x1010101
	global_atomic_add_f32 v217, v229, s[10:11] offset:640
	global_atomic_add_f32 v217, v230, s[10:11] offset:672
	s_mov_b64 exec, -1
	s_waitcnt vmcnt(10)
	v_add_u32_e32 v225, 0xb0000, v219
	v_add_u32_e32 v227, 0x58000, v218
	v_add_u32_e32 v226, 0x8000, v225
	v_add_u32_e32 v228, 0x4000, v227
	ds_write_b128 v221, v[14:17]
	ds_write_b128 v221, v[10:13] offset:16
	ds_read_b128 v[14:17], v222
	ds_read_b128 v[10:13], v222 offset:1152
	s_waitcnt lgkmcnt(0)
	v_pk_add_f32 v[14:15], v[14:15], v[200:201]
	v_pk_add_f32 v[16:17], v[16:17], v[202:203]
	v_pk_add_f32 v[10:11], v[10:11], v[204:205]
	v_pk_add_f32 v[12:13], v[12:13], v[206:207]
	global_store_dwordx4 v225, v[14:17], s[16:17]
	global_store_dwordx4 v226, v[10:13], s[16:17]
	v_cvt_pk_bf16_f32 v248, v14, v15
	v_cvt_pk_bf16_f32 v249, v16, v17
	v_cvt_pk_bf16_f32 v250, v10, v11
	v_cvt_pk_bf16_f32 v251, v12, v13
	v_mul_f32_e32 v229, v14, v14
	v_mul_f32_e32 v230, v10, v10
	v_fmac_f32_e32 v229, v15, v15
	v_fmac_f32_e32 v230, v11, v11
	v_fmac_f32_e32 v229, v16, v16
	v_fmac_f32_e32 v230, v12, v12
	v_fmac_f32_e32 v229, v17, v17
	v_fmac_f32_e32 v230, v13, v13
	global_store_dwordx2 v227, v[248:249], s[64:65]
	global_store_dwordx2 v228, v[250:251], s[64:65]
	ds_write_b128 v221, v[6:9]
	ds_write_b128 v221, v[2:5] offset:16
	ds_read_b128 v[6:9], v222
	ds_read_b128 v[2:5], v222 offset:1152
	s_waitcnt lgkmcnt(0)
	v_pk_add_f32 v[6:7], v[6:7], v[208:209]
	v_pk_add_f32 v[8:9], v[8:9], v[210:211]
	v_pk_add_f32 v[2:3], v[2:3], v[212:213]
	v_pk_add_f32 v[4:5], v[4:5], v[214:215]
	global_store_dwordx4 v225, v[6:9], s[16:17] offset:512
	global_store_dwordx4 v226, v[2:5], s[16:17] offset:512
	v_cvt_pk_bf16_f32 v248, v6, v7
	v_cvt_pk_bf16_f32 v249, v8, v9
	v_cvt_pk_bf16_f32 v250, v2, v3
	v_cvt_pk_bf16_f32 v251, v4, v5
	v_fmac_f32_e32 v229, v6, v6
	v_fmac_f32_e32 v230, v2, v2
	v_fmac_f32_e32 v229, v7, v7
	v_fmac_f32_e32 v230, v3, v3
	v_fmac_f32_e32 v229, v8, v8
	v_fmac_f32_e32 v230, v4, v4
	v_fmac_f32_e32 v229, v9, v9
	v_fmac_f32_e32 v230, v5, v5
	global_store_dwordx2 v227, v[248:249], s[64:65] offset:256
	global_store_dwordx2 v228, v[250:251], s[64:65] offset:256
	s_nop 1
	v_add_f32_dpp v229, v229, v229 quad_perm:[1,0,3,2] row_mask:0xf bank_mask:0xf
	v_add_f32_dpp v230, v230, v230 quad_perm:[1,0,3,2] row_mask:0xf bank_mask:0xf
	s_nop 0
	v_add_f32_dpp v229, v229, v229 quad_perm:[2,3,0,1] row_mask:0xf bank_mask:0xf
	v_add_f32_dpp v230, v230, v230 quad_perm:[2,3,0,1] row_mask:0xf bank_mask:0xf
	s_nop 0
	v_add_f32_dpp v229, v229, v229 row_half_mirror row_mask:0xf bank_mask:0xf
	v_add_f32_dpp v230, v230, v230 row_half_mirror row_mask:0xf bank_mask:0xf
	s_nop 0
	s_mov_b32 exec_lo, 0x1010101
	s_mov_b32 exec_hi, 0x1010101
	global_atomic_add_f32 v217, v229, s[10:11] offset:704
	global_atomic_add_f32 v217, v230, s[10:11] offset:736
	s_mov_b64 exec, -1
	s_and_b64 vcc, exec, s[4:5]
	s_mov_b64 s[4:5], -1
	s_cbranch_vccnz .LBB0_1125
	s_andn2_b64 vcc, exec, s[24:25]
	s_cbranch_vccnz .LBB0_1124
	s_barrier
	s_branch .LBB0_1124

; __device__ __forceinline__ unsigned pk(float lo, float hi) { return pg8::cvt_pk_bf16(lo, hi); }
; __device__ __forceinline__ float dot4(f32x4 v) { return (v[0] * v[0] + v[1] * v[1]) + (v[2] * v[2] + v[3] * v[3]); }
;     __device__ __forceinline__ void operator()(const pg8::f32x4 (&acc)[2][2][4][2], const pg8::Unit& u, int wr, int wc, int fr, int fq) const {
;         const int row0 = u.pm * 256 + wr * 64 + fr;
; #pragma unroll
;         for (int ai = 0; ai < 2; ++ai)
; #pragma unroll
;             for (int m = 0; m < 4; ++m) {
;                 const int row = row0 + ai * 128 + m * 16;
;                 const float* xi = (row < MP) ? xin_p + (size_t)row * DM : xin_s + (size_t)(row - MP) * DM;
;                 float sq = 0.f;
; #pragma unroll
;                 for (int bj = 0; bj < 2; ++bj) { const int col = u.pn * 256 + bj * 128 + wc * 32 + 8 * fq;
;                     const f32x4 a0 = *(const f32x4*)(xi + col) + acc[ai][bj][m][0], a1 = *(const f32x4*)(xi + col + 4) + acc[ai][bj][m][1];
;                     *(f32x4*)(xout + (size_t)row * DM + col) = a0; *(f32x4*)(xout + (size_t)row * DM + col + 4) = a1;
;                     u32x4 w; w.x = pk(a0[0], a0[1]); w.y = pk(a0[2], a0[3]); w.z = pk(a1[0], a1[1]); w.w = pk(a1[2], a1[3]);
;                     *(u32x4*)(xb + (size_t)row * DM + col) = w;
;                     sq += dot4(a0) + dot4(a1); }
;                 sq += __shfl_xor(sq, 16); sq += __shfl_xor(sq, 32);
;                 if (fq == 0) atomicAdd(ssout + row, sq);
;             }
;     }
.LBB0_1823:
	s_cmp_lt_u32 s40, 64
	s_cselect_b32 s98, s16, s8
	s_cselect_b32 s99, s17, s9
	s_cselect_b32 s100, 0, 0x4000
	v_and_b32_e32 v233, 63, v0
	v_lshrrev_b32_e32 v234, 3, v233
	v_and_b32_e32 v231, 7, v233
	v_and_b32_e32 v138, -16, v156
	v_add_u32_e32 v138, v138, v234
	v_lshl_add_u32 v138, s40, 8, v138
	v_and_b32_e32 v163, -32, v158
	v_lshl_add_u32 v163, v231, 2, v163
	v_lshl_or_b32 v163, s38, 8, v163
	v_lshlrev_b32_e32 v183, 2, v138
	v_lshlrev_b32_e32 v232, 1, v163
	v_lshl_add_u32 v220, v138, 11, v232
	v_lshlrev_b32_e32 v232, 2, v163
	v_lshl_add_u32 v221, v138, 12, v232
	v_subrev_u32_e32 v227, s100, v138
	v_lshl_add_u32 v222, v227, 12, v232
	v_lshrrev_b32_e32 v227, 6, v0
	v_mul_u32_u24_e32 v227, 0x900, v227
	v_add_u32_e32 v227, 0x21000, v227
	v_mul_u32_u24_e32 v229, 0x90, v234
	v_lshl_add_u32 v229, v231, 4, v229
	v_add_u32_e32 v224, v227, v229
	v_and_b32_e32 v229, 15, v233
	v_mul_u32_u24_e32 v229, 0x90, v229
	v_lshrrev_b32_e32 v230, 4, v233
	v_lshl_add_u32 v229, v230, 5, v229
	v_add_u32_e32 v223, v227, v229
	v_add_u32_e32 v226, 0x8000, v222
	global_load_dwordx4 v[148:151], v222, s[98:99]
	global_load_dwordx4 v[152:155], v226, s[98:99]
	global_load_dwordx4 v[164:167], v222, s[98:99] offset:512
	global_load_dwordx4 v[184:187], v226, s[98:99] offset:512
	v_add_u32_e32 v225, 0x10000, v222
	v_add_u32_e32 v226, 0x8000, v225
	global_load_dwordx4 v[188:191], v225, s[98:99]
	global_load_dwordx4 v[192:195], v226, s[98:99]
	global_load_dwordx4 v[196:199], v225, s[98:99] offset:512
	global_load_dwordx4 v[200:203], v226, s[98:99] offset:512
	v_add_u32_e32 v225, 0x20000, v222
	v_add_u32_e32 v226, 0x8000, v225
	global_load_dwordx4 v[204:207], v225, s[98:99]
	global_load_dwordx4 v[208:211], v226, s[98:99]
	global_load_dwordx4 v[212:215], v225, s[98:99] offset:512
	global_load_dwordx4 v[216:219], v226, s[98:99] offset:512
	s_waitcnt vmcnt(8)
	v_add_u32_e32 v228, 0x8000, v221
	v_add_u32_e32 v230, 0x4000, v220
	ds_write_b128 v223, v[126:129]
	ds_write_b128 v223, v[122:125] offset:16
	ds_read_b128 v[126:129], v224
	ds_read_b128 v[122:125], v224 offset:1152
	s_waitcnt lgkmcnt(0)
	v_pk_add_f32 v[126:127], v[126:127], v[148:149]
	v_pk_add_f32 v[128:129], v[128:129], v[150:151]
	v_pk_add_f32 v[122:123], v[122:123], v[152:153]
	v_pk_add_f32 v[124:125], v[124:125], v[154:155]
	global_store_dwordx4 v221, v[126:129], s[16:17]
	global_store_dwordx4 v228, v[122:125], s[16:17]
	v_cvt_pk_bf16_f32 v248, v126, v127
	v_cvt_pk_bf16_f32 v249, v128, v129
	v_cvt_pk_bf16_f32 v250, v122, v123
	v_cvt_pk_bf16_f32 v251, v124, v125
	v_mul_f32_e32 v231, v126, v126
	v_mul_f32_e32 v232, v122, v122
	v_fmac_f32_e32 v231, v127, v127
	v_fmac_f32_e32 v232, v123, v123
	v_fmac_f32_e32 v231, v128, v128
	v_fmac_f32_e32 v232, v124, v124
	v_fmac_f32_e32 v231, v129, v129
	v_fmac_f32_e32 v232, v125, v125
	global_store_dwordx2 v220, v[248:249], s[64:65]
	global_store_dwordx2 v230, v[250:251], s[64:65]
	ds_write_b128 v223, v[118:121]
	ds_write_b128 v223, v[114:117] offset:16
	ds_read_b128 v[118:121], v224
	ds_read_b128 v[114:117], v224 offset:1152
	s_waitcnt lgkmcnt(0)
	v_pk_add_f32 v[118:119], v[118:119], v[164:165]
	v_pk_add_f32 v[120:121], v[120:121], v[166:167]
	v_pk_add_f32 v[114:115], v[114:115], v[184:185]
	v_pk_add_f32 v[116:117], v[116:117], v[186:187]
	global_store_dwordx4 v221, v[118:121], s[16:17] offset:512
	global_store_dwordx4 v228, v[114:117], s[16:17] offset:512
	v_cvt_pk_bf16_f32 v248, v118, v119
	v_cvt_pk_bf16_f32 v249, v120, v121
	v_cvt_pk_bf16_f32 v250, v114, v115
	v_cvt_pk_bf16_f32 v251, v116, v117
	v_fmac_f32_e32 v231, v118, v118
	v_fmac_f32_e32 v232, v114, v114
	v_fmac_f32_e32 v231, v119, v119
	v_fmac_f32_e32 v232, v115, v115
	v_fmac_f32_e32 v231, v120, v120
	v_fmac_f32_e32 v232, v116, v116
	v_fmac_f32_e32 v231, v121, v121
	v_fmac_f32_e32 v232, v117, v117
	global_store_dwordx2 v220, v[248:249], s[64:65] offset:256
	global_store_dwordx2 v230, v[250:251], s[64:65] offset:256
	s_nop 1
	v_add_f32_dpp v231, v231, v231 quad_perm:[1,0,3,2] row_mask:0xf bank_mask:0xf
	v_add_f32_dpp v232, v232, v232 quad_perm:[1,0,3,2] row_mask:0xf bank_mask:0xf
	s_nop 0
	v_add_f32_dpp v231, v231, v231 quad_perm:[2,3,0,1] row_mask:0xf bank_mask:0xf
	v_add_f32_dpp v232, v232, v232 quad_perm:[2,3,0,1] row_mask:0xf bank_mask:0xf
	s_nop 0
	v_add_f32_dpp v231, v231, v231 row_half_mirror row_mask:0xf bank_mask:0xf
	v_add_f32_dpp v232, v232, v232 row_half_mirror row_mask:0xf bank_mask:0xf
	s_nop 0
	s_mov_b32 exec_lo, 0x1010101
	s_mov_b32 exec_hi, 0x1010101
	global_atomic_add_f32 v183, v231, s[10:11]
	global_atomic_add_f32 v183, v232, s[10:11] offset:32
	s_mov_b64 exec, -1
	v_add_u32_e32 v225, 0x30000, v222
	v_add_u32_e32 v226, 0x8000, v225
	global_load_dwordx4 v[148:151], v225, s[98:99]
	global_load_dwordx4 v[152:155], v226, s[98:99]
	global_load_dwordx4 v[164:167], v225, s[98:99] offset:512
	global_load_dwordx4 v[184:187], v226, s[98:99] offset:512
	s_waitcnt vmcnt(18)
	v_add_u32_e32 v227, 0x10000, v221
	v_add_u32_e32 v229, 0x8000, v220
	v_add_u32_e32 v228, 0x8000, v227
	v_add_u32_e32 v230, 0x4000, v229
	ds_write_b128 v223, v[110:113]
	ds_write_b128 v223, v[106:109] offset:16
	ds_read_b128 v[110:113], v224
	ds_read_b128 v[106:109], v224 offset:1152
	s_waitcnt lgkmcnt(0)
; __device__ __forceinline__ unsigned pk(float lo, float hi) { return pg8::cvt_pk_bf16(lo, hi); }
; __device__ __forceinline__ float dot4(f32x4 v) { return (v[0] * v[0] + v[1] * v[1]) + (v[2] * v[2] + v[3] * v[3]); }
;     __device__ __forceinline__ void operator()(const pg8::f32x4 (&acc)[2][2][4][2], const pg8::Unit& u, int wr, int wc, int fr, int fq) const {
;         const int row0 = u.pm * 256 + wr * 64 + fr;
; #pragma unroll
;         for (int ai = 0; ai < 2; ++ai)
; #pragma unroll
;             for (int m = 0; m < 4; ++m) {
;                 const int row = row0 + ai * 128 + m * 16;
;                 const float* xi = (row < MP) ? xin_p + (size_t)row * DM : xin_s + (size_t)(row - MP) * DM;
;                 float sq = 0.f;
; #pragma unroll
;                 for (int bj = 0; bj < 2; ++bj) { const int col = u.pn * 256 + bj * 128 + wc * 32 + 8 * fq;
;                     const f32x4 a0 = *(const f32x4*)(xi + col) + acc[ai][bj][m][0], a1 = *(const f32x4*)(xi + col + 4) + acc[ai][bj][m][1];
;                     *(f32x4*)(xout + (size_t)row * DM + col) = a0; *(f32x4*)(xout + (size_t)row * DM + col + 4) = a1;
;                     u32x4 w; w.x = pk(a0[0], a0[1]); w.y = pk(a0[2], a0[3]); w.z = pk(a1[0], a1[1]); w.w = pk(a1[2], a1[3]);
;                     *(u32x4*)(xb + (size_t)row * DM + col) = w;
;                     sq += dot4(a0) + dot4(a1); }
;                 sq += __shfl_xor(sq, 16); sq += __shfl_xor(sq, 32);
;                 if (fq == 0) atomicAdd(ssout + row, sq);
;             }
;     }
	v_pk_add_f32 v[110:111], v[110:111], v[188:189]
	v_pk_add_f32 v[112:113], v[112:113], v[190:191]
	v_pk_add_f32 v[106:107], v[106:107], v[192:193]
	v_pk_add_f32 v[108:109], v[108:109], v[194:195]
	global_store_dwordx4 v227, v[110:113], s[16:17]
	global_store_dwordx4 v228, v[106:109], s[16:17]
	v_cvt_pk_bf16_f32 v248, v110, v111
	v_cvt_pk_bf16_f32 v249, v112, v113
	v_cvt_pk_bf16_f32 v250, v106, v107
	v_cvt_pk_bf16_f32 v251, v108, v109
	v_mul_f32_e32 v231, v110, v110
	v_mul_f32_e32 v232, v106, v106
	v_fmac_f32_e32 v231, v111, v111
	v_fmac_f32_e32 v232, v107, v107
	v_fmac_f32_e32 v231, v112, v112
	v_fmac_f32_e32 v232, v108, v108
	v_fmac_f32_e32 v231, v113, v113
	v_fmac_f32_e32 v232, v109, v109
	global_store_dwordx2 v229, v[248:249], s[64:65]
	global_store_dwordx2 v230, v[250:251], s[64:65]
	ds_write_b128 v223, v[102:105]
	ds_write_b128 v223, v[98:101] offset:16
	ds_read_b128 v[102:105], v224
	ds_read_b128 v[98:101], v224 offset:1152
	s_waitcnt lgkmcnt(0)
	v_pk_add_f32 v[102:103], v[102:103], v[196:197]
	v_pk_add_f32 v[104:105], v[104:105], v[198:199]
	v_pk_add_f32 v[98:99], v[98:99], v[200:201]
	v_pk_add_f32 v[100:101], v[100:101], v[202:203]
	global_store_dwordx4 v227, v[102:105], s[16:17] offset:512
	global_store_dwordx4 v228, v[98:101], s[16:17] offset:512
	v_cvt_pk_bf16_f32 v248, v102, v103
	v_cvt_pk_bf16_f32 v249, v104, v105
	v_cvt_pk_bf16_f32 v250, v98, v99
	v_cvt_pk_bf16_f32 v251, v100, v101
	v_fmac_f32_e32 v231, v102, v102
	v_fmac_f32_e32 v232, v98, v98
	v_fmac_f32_e32 v231, v103, v103
	v_fmac_f32_e32 v232, v99, v99
	v_fmac_f32_e32 v231, v104, v104
	v_fmac_f32_e32 v232, v100, v100
	v_fmac_f32_e32 v231, v105, v105
	v_fmac_f32_e32 v232, v101, v101
	global_store_dwordx2 v229, v[248:249], s[64:65] offset:256
	global_store_dwordx2 v230, v[250:251], s[64:65] offset:256
	s_nop 1
	v_add_f32_dpp v231, v231, v231 quad_perm:[1,0,3,2] row_mask:0xf bank_mask:0xf
	v_add_f32_dpp v232, v232, v232 quad_perm:[1,0,3,2] row_mask:0xf bank_mask:0xf
	s_nop 0
	v_add_f32_dpp v231, v231, v231 quad_perm:[2,3,0,1] row_mask:0xf bank_mask:0xf
	v_add_f32_dpp v232, v232, v232 quad_perm:[2,3,0,1] row_mask:0xf bank_mask:0xf
	s_nop 0
	v_add_f32_dpp v231, v231, v231 row_half_mirror row_mask:0xf bank_mask:0xf
	v_add_f32_dpp v232, v232, v232 row_half_mirror row_mask:0xf bank_mask:0xf
	s_nop 0
	s_mov_b32 exec_lo, 0x1010101
	s_mov_b32 exec_hi, 0x1010101
	global_atomic_add_f32 v183, v231, s[10:11] offset:64
	global_atomic_add_f32 v183, v232, s[10:11] offset:96
	s_mov_b64 exec, -1
	v_add_u32_e32 v225, 0x80000, v222
	v_add_u32_e32 v226, 0x8000, v225
	global_load_dwordx4 v[188:191], v225, s[98:99]
	global_load_dwordx4 v[192:195], v226, s[98:99]
	global_load_dwordx4 v[196:199], v225, s[98:99] offset:512
	global_load_dwordx4 v[200:203], v226, s[98:99] offset:512
	s_waitcnt vmcnt(28)
	v_add_u32_e32 v227, 0x20000, v221
	v_add_u32_e32 v229, 0x10000, v220
	v_add_u32_e32 v228, 0x8000, v227
	v_add_u32_e32 v230, 0x4000, v229
	ds_write_b128 v223, v[94:97]
	ds_write_b128 v223, v[90:93] offset:16
	ds_read_b128 v[94:97], v224
	ds_read_b128 v[90:93], v224 offset:1152
	s_waitcnt lgkmcnt(0)
	v_pk_add_f32 v[94:95], v[94:95], v[204:205]
	v_pk_add_f32 v[96:97], v[96:97], v[206:207]
	v_pk_add_f32 v[90:91], v[90:91], v[208:209]
	v_pk_add_f32 v[92:93], v[92:93], v[210:211]
	global_store_dwordx4 v227, v[94:97], s[16:17]
	global_store_dwordx4 v228, v[90:93], s[16:17]
	v_cvt_pk_bf16_f32 v248, v94, v95
	v_cvt_pk_bf16_f32 v249, v96, v97
	v_cvt_pk_bf16_f32 v250, v90, v91
	v_cvt_pk_bf16_f32 v251, v92, v93
	v_mul_f32_e32 v231, v94, v94
	v_mul_f32_e32 v232, v90, v90
	v_fmac_f32_e32 v231, v95, v95
	v_fmac_f32_e32 v232, v91, v91
	v_fmac_f32_e32 v231, v96, v96
	v_fmac_f32_e32 v232, v92, v92
	v_fmac_f32_e32 v231, v97, v97
	v_fmac_f32_e32 v232, v93, v93
	global_store_dwordx2 v229, v[248:249], s[64:65]
	global_store_dwordx2 v230, v[250:251], s[64:65]
	ds_write_b128 v223, v[86:89]
	ds_write_b128 v223, v[82:85] offset:16
	ds_read_b128 v[86:89], v224
	ds_read_b128 v[82:85], v224 offset:1152
	s_waitcnt lgkmcnt(0)
	v_pk_add_f32 v[86:87], v[86:87], v[212:213]
	v_pk_add_f32 v[88:89], v[88:89], v[214:215]
	v_pk_add_f32 v[82:83], v[82:83], v[216:217]
	v_pk_add_f32 v[84:85], v[84:85], v[218:219]
	global_store_dwordx4 v227, v[86:89], s[16:17] offset:512
	global_store_dwordx4 v228, v[82:85], s[16:17] offset:512
	v_cvt_pk_bf16_f32 v248, v86, v87
	v_cvt_pk_bf16_f32 v249, v88, v89
	v_cvt_pk_bf16_f32 v250, v82, v83
	v_cvt_pk_bf16_f32 v251, v84, v85
	v_fmac_f32_e32 v231, v86, v86
	v_fmac_f32_e32 v232, v82, v82
	v_fmac_f32_e32 v231, v87, v87
	v_fmac_f32_e32 v232, v83, v83
	v_fmac_f32_e32 v231, v88, v88
	v_fmac_f32_e32 v232, v84, v84
	v_fmac_f32_e32 v231, v89, v89
	v_fmac_f32_e32 v232, v85, v85
	global_store_dwordx2 v229, v[248:249], s[64:65] offset:256
	global_store_dwordx2 v230, v[250:251], s[64:65] offset:256
	s_nop 1
	v_add_f32_dpp v231, v231, v231 quad_perm:[1,0,3,2] row_mask:0xf bank_mask:0xf
	v_add_f32_dpp v232, v232, v232 quad_perm:[1,0,3,2] row_mask:0xf bank_mask:0xf
	s_nop 0
	v_add_f32_dpp v231, v231, v231 quad_perm:[2,3,0,1] row_mask:0xf bank_mask:0xf
	v_add_f32_dpp v232, v232, v232 quad_perm:[2,3,0,1] row_mask:0xf bank_mask:0xf
	s_nop 0
	v_add_f32_dpp v231, v231, v231 row_half_mirror row_mask:0xf bank_mask:0xf
	v_add_f32_dpp v232, v232, v232 row_half_mirror row_mask:0xf bank_mask:0xf
	s_nop 0
	s_mov_b32 exec_lo, 0x1010101
	s_mov_b32 exec_hi, 0x1010101
	global_atomic_add_f32 v183, v231, s[10:11] offset:128
	global_atomic_add_f32 v183, v232, s[10:11] offset:160
	s_mov_b64 exec, -1
	v_add_u32_e32 v225, 0x90000, v222
	v_add_u32_e32 v226, 0x8000, v225
	global_load_dwordx4 v[204:207], v225, s[98:99]
	global_load_dwordx4 v[208:211], v226, s[98:99]
	global_load_dwordx4 v[212:215], v225, s[98:99] offset:512
	global_load_dwordx4 v[216:219], v226, s[98:99] offset:512
	s_waitcnt vmcnt(28)
; __device__ __forceinline__ unsigned pk(float lo, float hi) { return pg8::cvt_pk_bf16(lo, hi); }
; __device__ __forceinline__ float dot4(f32x4 v) { return (v[0] * v[0] + v[1] * v[1]) + (v[2] * v[2] + v[3] * v[3]); }
;     __device__ __forceinline__ void operator()(const pg8::f32x4 (&acc)[2][2][4][2], const pg8::Unit& u, int wr, int wc, int fr, int fq) const {
;         const int row0 = u.pm * 256 + wr * 64 + fr;
; #pragma unroll
;         for (int ai = 0; ai < 2; ++ai)
; #pragma unroll
;             for (int m = 0; m < 4; ++m) {
;                 const int row = row0 + ai * 128 + m * 16;
;                 const float* xi = (row < MP) ? xin_p + (size_t)row * DM : xin_s + (size_t)(row - MP) * DM;
;                 float sq = 0.f;
; #pragma unroll
;                 for (int bj = 0; bj < 2; ++bj) { const int col = u.pn * 256 + bj * 128 + wc * 32 + 8 * fq;
;                     const f32x4 a0 = *(const f32x4*)(xi + col) + acc[ai][bj][m][0], a1 = *(const f32x4*)(xi + col + 4) + acc[ai][bj][m][1];
;                     *(f32x4*)(xout + (size_t)row * DM + col) = a0; *(f32x4*)(xout + (size_t)row * DM + col + 4) = a1;
;                     u32x4 w; w.x = pk(a0[0], a0[1]); w.y = pk(a0[2], a0[3]); w.z = pk(a1[0], a1[1]); w.w = pk(a1[2], a1[3]);
;                     *(u32x4*)(xb + (size_t)row * DM + col) = w;
;                     sq += dot4(a0) + dot4(a1); }
;                 sq += __shfl_xor(sq, 16); sq += __shfl_xor(sq, 32);
;                 if (fq == 0) atomicAdd(ssout + row, sq);
;             }
;     }
	v_add_u32_e32 v227, 0x30000, v221
	v_add_u32_e32 v229, 0x18000, v220
	v_add_u32_e32 v228, 0x8000, v227
	v_add_u32_e32 v230, 0x4000, v229
	ds_write_b128 v223, v[78:81]
	ds_write_b128 v223, v[74:77] offset:16
	ds_read_b128 v[78:81], v224
	ds_read_b128 v[74:77], v224 offset:1152
	s_waitcnt lgkmcnt(0)
	v_pk_add_f32 v[78:79], v[78:79], v[148:149]
	v_pk_add_f32 v[80:81], v[80:81], v[150:151]
	v_pk_add_f32 v[74:75], v[74:75], v[152:153]
	v_pk_add_f32 v[76:77], v[76:77], v[154:155]
	global_store_dwordx4 v227, v[78:81], s[16:17]
	global_store_dwordx4 v228, v[74:77], s[16:17]
	v_cvt_pk_bf16_f32 v248, v78, v79
	v_cvt_pk_bf16_f32 v249, v80, v81
	v_cvt_pk_bf16_f32 v250, v74, v75
	v_cvt_pk_bf16_f32 v251, v76, v77
	v_mul_f32_e32 v231, v78, v78
	v_mul_f32_e32 v232, v74, v74
	v_fmac_f32_e32 v231, v79, v79
	v_fmac_f32_e32 v232, v75, v75
	v_fmac_f32_e32 v231, v80, v80
	v_fmac_f32_e32 v232, v76, v76
	v_fmac_f32_e32 v231, v81, v81
	v_fmac_f32_e32 v232, v77, v77
	global_store_dwordx2 v229, v[248:249], s[64:65]
	global_store_dwordx2 v230, v[250:251], s[64:65]
	ds_write_b128 v223, v[70:73]
	ds_write_b128 v223, v[66:69] offset:16
	ds_read_b128 v[70:73], v224
	ds_read_b128 v[66:69], v224 offset:1152
	s_waitcnt lgkmcnt(0)
	v_pk_add_f32 v[70:71], v[70:71], v[164:165]
	v_pk_add_f32 v[72:73], v[72:73], v[166:167]
	v_pk_add_f32 v[66:67], v[66:67], v[184:185]
	v_pk_add_f32 v[68:69], v[68:69], v[186:187]
	global_store_dwordx4 v227, v[70:73], s[16:17] offset:512
	global_store_dwordx4 v228, v[66:69], s[16:17] offset:512
	v_cvt_pk_bf16_f32 v248, v70, v71
	v_cvt_pk_bf16_f32 v249, v72, v73
	v_cvt_pk_bf16_f32 v250, v66, v67
	v_cvt_pk_bf16_f32 v251, v68, v69
	v_fmac_f32_e32 v231, v70, v70
	v_fmac_f32_e32 v232, v66, v66
	v_fmac_f32_e32 v231, v71, v71
	v_fmac_f32_e32 v232, v67, v67
	v_fmac_f32_e32 v231, v72, v72
	v_fmac_f32_e32 v232, v68, v68
	v_fmac_f32_e32 v231, v73, v73
	v_fmac_f32_e32 v232, v69, v69
	global_store_dwordx2 v229, v[248:249], s[64:65] offset:256
	global_store_dwordx2 v230, v[250:251], s[64:65] offset:256
	s_nop 1
	v_add_f32_dpp v231, v231, v231 quad_perm:[1,0,3,2] row_mask:0xf bank_mask:0xf
	v_add_f32_dpp v232, v232, v232 quad_perm:[1,0,3,2] row_mask:0xf bank_mask:0xf
	s_nop 0
	v_add_f32_dpp v231, v231, v231 quad_perm:[2,3,0,1] row_mask:0xf bank_mask:0xf
	v_add_f32_dpp v232, v232, v232 quad_perm:[2,3,0,1] row_mask:0xf bank_mask:0xf
	s_nop 0
	v_add_f32_dpp v231, v231, v231 row_half_mirror row_mask:0xf bank_mask:0xf
	v_add_f32_dpp v232, v232, v232 row_half_mirror row_mask:0xf bank_mask:0xf
	s_nop 0
	s_mov_b32 exec_lo, 0x1010101
	s_mov_b32 exec_hi, 0x1010101
	global_atomic_add_f32 v183, v231, s[10:11] offset:192
	global_atomic_add_f32 v183, v232, s[10:11] offset:224
	s_mov_b64 exec, -1
	v_add_u32_e32 v225, 0xa0000, v222
	v_add_u32_e32 v226, 0x8000, v225
	global_load_dwordx4 v[148:151], v225, s[98:99]
	global_load_dwordx4 v[152:155], v226, s[98:99]
	global_load_dwordx4 v[164:167], v225, s[98:99] offset:512
	global_load_dwordx4 v[184:187], v226, s[98:99] offset:512
	s_waitcnt vmcnt(28)
	v_add_u32_e32 v227, 0x80000, v221
	v_add_u32_e32 v229, 0x40000, v220
	v_add_u32_e32 v228, 0x8000, v227
	v_add_u32_e32 v230, 0x4000, v229
	ds_write_b128 v223, v[62:65]
	ds_write_b128 v223, v[58:61] offset:16
	ds_read_b128 v[62:65], v224
	ds_read_b128 v[58:61], v224 offset:1152
	s_waitcnt lgkmcnt(0)
	v_pk_add_f32 v[62:63], v[62:63], v[188:189]
	v_pk_add_f32 v[64:65], v[64:65], v[190:191]
	v_pk_add_f32 v[58:59], v[58:59], v[192:193]
	v_pk_add_f32 v[60:61], v[60:61], v[194:195]
	global_store_dwordx4 v227, v[62:65], s[16:17]
	global_store_dwordx4 v228, v[58:61], s[16:17]
	v_cvt_pk_bf16_f32 v248, v62, v63
	v_cvt_pk_bf16_f32 v249, v64, v65
	v_cvt_pk_bf16_f32 v250, v58, v59
	v_cvt_pk_bf16_f32 v251, v60, v61
	v_mul_f32_e32 v231, v62, v62
	v_mul_f32_e32 v232, v58, v58
	v_fmac_f32_e32 v231, v63, v63
	v_fmac_f32_e32 v232, v59, v59
	v_fmac_f32_e32 v231, v64, v64
	v_fmac_f32_e32 v232, v60, v60
	v_fmac_f32_e32 v231, v65, v65
	v_fmac_f32_e32 v232, v61, v61
	global_store_dwordx2 v229, v[248:249], s[64:65]
	global_store_dwordx2 v230, v[250:251], s[64:65]
	ds_write_b128 v223, v[54:57]
	ds_write_b128 v223, v[50:53] offset:16
	ds_read_b128 v[54:57], v224
	ds_read_b128 v[50:53], v224 offset:1152
	s_waitcnt lgkmcnt(0)
	v_pk_add_f32 v[54:55], v[54:55], v[196:197]
	v_pk_add_f32 v[56:57], v[56:57], v[198:199]
	v_pk_add_f32 v[50:51], v[50:51], v[200:201]
	v_pk_add_f32 v[52:53], v[52:53], v[202:203]
	global_store_dwordx4 v227, v[54:57], s[16:17] offset:512
	global_store_dwordx4 v228, v[50:53], s[16:17] offset:512
	v_cvt_pk_bf16_f32 v248, v54, v55
	v_cvt_pk_bf16_f32 v249, v56, v57
	v_cvt_pk_bf16_f32 v250, v50, v51
	v_cvt_pk_bf16_f32 v251, v52, v53
	v_fmac_f32_e32 v231, v54, v54
	v_fmac_f32_e32 v232, v50, v50
	v_fmac_f32_e32 v231, v55, v55
	v_fmac_f32_e32 v232, v51, v51
	v_fmac_f32_e32 v231, v56, v56
	v_fmac_f32_e32 v232, v52, v52
	v_fmac_f32_e32 v231, v57, v57
	v_fmac_f32_e32 v232, v53, v53
	global_store_dwordx2 v229, v[248:249], s[64:65] offset:256
	global_store_dwordx2 v230, v[250:251], s[64:65] offset:256
	s_nop 1
	v_add_f32_dpp v231, v231, v231 quad_perm:[1,0,3,2] row_mask:0xf bank_mask:0xf
	v_add_f32_dpp v232, v232, v232 quad_perm:[1,0,3,2] row_mask:0xf bank_mask:0xf
	s_nop 0
	v_add_f32_dpp v231, v231, v231 quad_perm:[2,3,0,1] row_mask:0xf bank_mask:0xf
	v_add_f32_dpp v232, v232, v232 quad_perm:[2,3,0,1] row_mask:0xf bank_mask:0xf
	s_nop 0
	v_add_f32_dpp v231, v231, v231 row_half_mirror row_mask:0xf bank_mask:0xf
	v_add_f32_dpp v232, v232, v232 row_half_mirror row_mask:0xf bank_mask:0xf
	s_nop 0
	s_mov_b32 exec_lo, 0x1010101
	s_mov_b32 exec_hi, 0x1010101
	global_atomic_add_f32 v183, v231, s[10:11] offset:512
	global_atomic_add_f32 v183, v232, s[10:11] offset:544
	s_mov_b64 exec, -1
	v_add_u32_e32 v225, 0xb0000, v222
	v_add_u32_e32 v226, 0x8000, v225
	global_load_dwordx4 v[188:191], v225, s[98:99]
	global_load_dwordx4 v[192:195], v226, s[98:99]
	global_load_dwordx4 v[196:199], v225, s[98:99] offset:512
	global_load_dwordx4 v[200:203], v226, s[98:99] offset:512
	s_waitcnt vmcnt(28)
; __device__ __forceinline__ unsigned pk(float lo, float hi) { return pg8::cvt_pk_bf16(lo, hi); }
; __device__ __forceinline__ float dot4(f32x4 v) { return (v[0] * v[0] + v[1] * v[1]) + (v[2] * v[2] + v[3] * v[3]); }
;     __device__ __forceinline__ void operator()(const pg8::f32x4 (&acc)[2][2][4][2], const pg8::Unit& u, int wr, int wc, int fr, int fq) const {
;         const int row0 = u.pm * 256 + wr * 64 + fr;
; #pragma unroll
;         for (int ai = 0; ai < 2; ++ai)
; #pragma unroll
;             for (int m = 0; m < 4; ++m) {
;                 const int row = row0 + ai * 128 + m * 16;
;                 const float* xi = (row < MP) ? xin_p + (size_t)row * DM : xin_s + (size_t)(row - MP) * DM;
;                 float sq = 0.f;
; #pragma unroll
;                 for (int bj = 0; bj < 2; ++bj) { const int col = u.pn * 256 + bj * 128 + wc * 32 + 8 * fq;
;                     const f32x4 a0 = *(const f32x4*)(xi + col) + acc[ai][bj][m][0], a1 = *(const f32x4*)(xi + col + 4) + acc[ai][bj][m][1];
;                     *(f32x4*)(xout + (size_t)row * DM + col) = a0; *(f32x4*)(xout + (size_t)row * DM + col + 4) = a1;
;                     u32x4 w; w.x = pk(a0[0], a0[1]); w.y = pk(a0[2], a0[3]); w.z = pk(a1[0], a1[1]); w.w = pk(a1[2], a1[3]);
;                     *(u32x4*)(xb + (size_t)row * DM + col) = w;
;                     sq += dot4(a0) + dot4(a1); }
;                 sq += __shfl_xor(sq, 16); sq += __shfl_xor(sq, 32);
;                 if (fq == 0) atomicAdd(ssout + row, sq);
;             }
;     }
	v_add_u32_e32 v227, 0x90000, v221
	v_add_u32_e32 v229, 0x48000, v220
	v_add_u32_e32 v228, 0x8000, v227
	v_add_u32_e32 v230, 0x4000, v229
	ds_write_b128 v223, v[46:49]
	ds_write_b128 v223, v[42:45] offset:16
	ds_read_b128 v[46:49], v224
	ds_read_b128 v[42:45], v224 offset:1152
	s_waitcnt lgkmcnt(0)
	v_pk_add_f32 v[46:47], v[46:47], v[204:205]
	v_pk_add_f32 v[48:49], v[48:49], v[206:207]
	v_pk_add_f32 v[42:43], v[42:43], v[208:209]
	v_pk_add_f32 v[44:45], v[44:45], v[210:211]
	global_store_dwordx4 v227, v[46:49], s[16:17]
	global_store_dwordx4 v228, v[42:45], s[16:17]
	v_cvt_pk_bf16_f32 v248, v46, v47
	v_cvt_pk_bf16_f32 v249, v48, v49
	v_cvt_pk_bf16_f32 v250, v42, v43
	v_cvt_pk_bf16_f32 v251, v44, v45
	v_mul_f32_e32 v231, v46, v46
	v_mul_f32_e32 v232, v42, v42
	v_fmac_f32_e32 v231, v47, v47
	v_fmac_f32_e32 v232, v43, v43
	v_fmac_f32_e32 v231, v48, v48
	v_fmac_f32_e32 v232, v44, v44
	v_fmac_f32_e32 v231, v49, v49
	v_fmac_f32_e32 v232, v45, v45
	global_store_dwordx2 v229, v[248:249], s[64:65]
	global_store_dwordx2 v230, v[250:251], s[64:65]
	ds_write_b128 v223, v[38:41]
	ds_write_b128 v223, v[34:37] offset:16
	ds_read_b128 v[38:41], v224
	ds_read_b128 v[34:37], v224 offset:1152
	s_waitcnt lgkmcnt(0)
	v_pk_add_f32 v[38:39], v[38:39], v[212:213]
	v_pk_add_f32 v[40:41], v[40:41], v[214:215]
	v_pk_add_f32 v[34:35], v[34:35], v[216:217]
	v_pk_add_f32 v[36:37], v[36:37], v[218:219]
	global_store_dwordx4 v227, v[38:41], s[16:17] offset:512
	global_store_dwordx4 v228, v[34:37], s[16:17] offset:512
	v_cvt_pk_bf16_f32 v248, v38, v39
	v_cvt_pk_bf16_f32 v249, v40, v41
	v_cvt_pk_bf16_f32 v250, v34, v35
	v_cvt_pk_bf16_f32 v251, v36, v37
	v_fmac_f32_e32 v231, v38, v38
	v_fmac_f32_e32 v232, v34, v34
	v_fmac_f32_e32 v231, v39, v39
	v_fmac_f32_e32 v232, v35, v35
	v_fmac_f32_e32 v231, v40, v40
	v_fmac_f32_e32 v232, v36, v36
	v_fmac_f32_e32 v231, v41, v41
	v_fmac_f32_e32 v232, v37, v37
	global_store_dwordx2 v229, v[248:249], s[64:65] offset:256
	global_store_dwordx2 v230, v[250:251], s[64:65] offset:256
	s_nop 1
	v_add_f32_dpp v231, v231, v231 quad_perm:[1,0,3,2] row_mask:0xf bank_mask:0xf
	v_add_f32_dpp v232, v232, v232 quad_perm:[1,0,3,2] row_mask:0xf bank_mask:0xf
	s_nop 0
	v_add_f32_dpp v231, v231, v231 quad_perm:[2,3,0,1] row_mask:0xf bank_mask:0xf
	v_add_f32_dpp v232, v232, v232 quad_perm:[2,3,0,1] row_mask:0xf bank_mask:0xf
	s_nop 0
	v_add_f32_dpp v231, v231, v231 row_half_mirror row_mask:0xf bank_mask:0xf
	v_add_f32_dpp v232, v232, v232 row_half_mirror row_mask:0xf bank_mask:0xf
	s_nop 0
	s_mov_b32 exec_lo, 0x1010101
	s_mov_b32 exec_hi, 0x1010101
	global_atomic_add_f32 v183, v231, s[10:11] offset:576
	global_atomic_add_f32 v183, v232, s[10:11] offset:608
	s_mov_b64 exec, -1
	s_waitcnt vmcnt(24)
	v_add_u32_e32 v227, 0xa0000, v221
	v_add_u32_e32 v229, 0x50000, v220
	v_add_u32_e32 v228, 0x8000, v227
	v_add_u32_e32 v230, 0x4000, v229
	ds_write_b128 v223, v[30:33]
	ds_write_b128 v223, v[26:29] offset:16
	ds_read_b128 v[30:33], v224
	ds_read_b128 v[26:29], v224 offset:1152
	s_waitcnt lgkmcnt(0)
	v_pk_add_f32 v[30:31], v[30:31], v[148:149]
	v_pk_add_f32 v[32:33], v[32:33], v[150:151]
	v_pk_add_f32 v[26:27], v[26:27], v[152:153]
	v_pk_add_f32 v[28:29], v[28:29], v[154:155]
	global_store_dwordx4 v227, v[30:33], s[16:17]
	global_store_dwordx4 v228, v[26:29], s[16:17]
	v_cvt_pk_bf16_f32 v248, v30, v31
	v_cvt_pk_bf16_f32 v249, v32, v33
	v_cvt_pk_bf16_f32 v250, v26, v27
	v_cvt_pk_bf16_f32 v251, v28, v29
	v_mul_f32_e32 v231, v30, v30
	v_mul_f32_e32 v232, v26, v26
	v_fmac_f32_e32 v231, v31, v31
	v_fmac_f32_e32 v232, v27, v27
	v_fmac_f32_e32 v231, v32, v32
	v_fmac_f32_e32 v232, v28, v28
	v_fmac_f32_e32 v231, v33, v33
	v_fmac_f32_e32 v232, v29, v29
	global_store_dwordx2 v229, v[248:249], s[64:65]
	global_store_dwordx2 v230, v[250:251], s[64:65]
	ds_write_b128 v223, v[22:25]
	ds_write_b128 v223, v[18:21] offset:16
	ds_read_b128 v[22:25], v224
	ds_read_b128 v[18:21], v224 offset:1152
	s_waitcnt lgkmcnt(0)
; __device__ __forceinline__ unsigned pk(float lo, float hi) { return pg8::cvt_pk_bf16(lo, hi); }
; __device__ __forceinline__ float dot4(f32x4 v) { return (v[0] * v[0] + v[1] * v[1]) + (v[2] * v[2] + v[3] * v[3]); }
;     __device__ __forceinline__ void operator()(const pg8::f32x4 (&acc)[2][2][4][2], const pg8::Unit& u, int wr, int wc, int fr, int fq) const {
;         const int row0 = u.pm * 256 + wr * 64 + fr;
; #pragma unroll
;         for (int ai = 0; ai < 2; ++ai)
; #pragma unroll
;             for (int m = 0; m < 4; ++m) {
;                 const int row = row0 + ai * 128 + m * 16;
;                 const float* xi = (row < MP) ? xin_p + (size_t)row * DM : xin_s + (size_t)(row - MP) * DM;
;                 float sq = 0.f;
; #pragma unroll
;                 for (int bj = 0; bj < 2; ++bj) { const int col = u.pn * 256 + bj * 128 + wc * 32 + 8 * fq;
;                     const f32x4 a0 = *(const f32x4*)(xi + col) + acc[ai][bj][m][0], a1 = *(const f32x4*)(xi + col + 4) + acc[ai][bj][m][1];
;                     *(f32x4*)(xout + (size_t)row * DM + col) = a0; *(f32x4*)(xout + (size_t)row * DM + col + 4) = a1;
;                     u32x4 w; w.x = pk(a0[0], a0[1]); w.y = pk(a0[2], a0[3]); w.z = pk(a1[0], a1[1]); w.w = pk(a1[2], a1[3]);
;                     *(u32x4*)(xb + (size_t)row * DM + col) = w;
;                     sq += dot4(a0) + dot4(a1); }
;                 sq += __shfl_xor(sq, 16); sq += __shfl_xor(sq, 32);
;                 if (fq == 0) atomicAdd(ssout + row, sq);
;             }
;     }
	v_pk_add_f32 v[22:23], v[22:23], v[164:165]
	v_pk_add_f32 v[24:25], v[24:25], v[166:167]
	v_pk_add_f32 v[18:19], v[18:19], v[184:185]
	v_pk_add_f32 v[20:21], v[20:21], v[186:187]
	global_store_dwordx4 v227, v[22:25], s[16:17] offset:512
	global_store_dwordx4 v228, v[18:21], s[16:17] offset:512
	v_cvt_pk_bf16_f32 v248, v22, v23
	v_cvt_pk_bf16_f32 v249, v24, v25
	v_cvt_pk_bf16_f32 v250, v18, v19
	v_cvt_pk_bf16_f32 v251, v20, v21
	v_fmac_f32_e32 v231, v22, v22
	v_fmac_f32_e32 v232, v18, v18
	v_fmac_f32_e32 v231, v23, v23
	v_fmac_f32_e32 v232, v19, v19
	v_fmac_f32_e32 v231, v24, v24
	v_fmac_f32_e32 v232, v20, v20
	v_fmac_f32_e32 v231, v25, v25
	v_fmac_f32_e32 v232, v21, v21
	global_store_dwordx2 v229, v[248:249], s[64:65] offset:256
	global_store_dwordx2 v230, v[250:251], s[64:65] offset:256
	s_nop 1
	v_add_f32_dpp v231, v231, v231 quad_perm:[1,0,3,2] row_mask:0xf bank_mask:0xf
	v_add_f32_dpp v232, v232, v232 quad_perm:[1,0,3,2] row_mask:0xf bank_mask:0xf
	s_nop 0
	v_add_f32_dpp v231, v231, v231 quad_perm:[2,3,0,1] row_mask:0xf bank_mask:0xf
	v_add_f32_dpp v232, v232, v232 quad_perm:[2,3,0,1] row_mask:0xf bank_mask:0xf
	s_nop 0
	v_add_f32_dpp v231, v231, v231 row_half_mirror row_mask:0xf bank_mask:0xf
	v_add_f32_dpp v232, v232, v232 row_half_mirror row_mask:0xf bank_mask:0xf
	s_nop 0
	s_mov_b32 exec_lo, 0x1010101
	s_mov_b32 exec_hi, 0x1010101
	global_atomic_add_f32 v183, v231, s[10:11] offset:640
	global_atomic_add_f32 v183, v232, s[10:11] offset:672
	s_mov_b64 exec, -1
	s_waitcnt vmcnt(20)
	v_add_u32_e32 v227, 0xb0000, v221
	v_add_u32_e32 v229, 0x58000, v220
	v_add_u32_e32 v228, 0x8000, v227
	v_add_u32_e32 v230, 0x4000, v229
	ds_write_b128 v223, v[14:17]
	ds_write_b128 v223, v[10:13] offset:16
	ds_read_b128 v[14:17], v224
	ds_read_b128 v[10:13], v224 offset:1152
	s_waitcnt lgkmcnt(0)
	v_pk_add_f32 v[14:15], v[14:15], v[188:189]
	v_pk_add_f32 v[16:17], v[16:17], v[190:191]
	v_pk_add_f32 v[10:11], v[10:11], v[192:193]
	v_pk_add_f32 v[12:13], v[12:13], v[194:195]
	global_store_dwordx4 v227, v[14:17], s[16:17]
	global_store_dwordx4 v228, v[10:13], s[16:17]
	v_cvt_pk_bf16_f32 v248, v14, v15
	v_cvt_pk_bf16_f32 v249, v16, v17
	v_cvt_pk_bf16_f32 v250, v10, v11
	v_cvt_pk_bf16_f32 v251, v12, v13
	v_mul_f32_e32 v231, v14, v14
	v_mul_f32_e32 v232, v10, v10
	v_fmac_f32_e32 v231, v15, v15
	v_fmac_f32_e32 v232, v11, v11
	v_fmac_f32_e32 v231, v16, v16
	v_fmac_f32_e32 v232, v12, v12
	v_fmac_f32_e32 v231, v17, v17
	v_fmac_f32_e32 v232, v13, v13
	global_store_dwordx2 v229, v[248:249], s[64:65]
	global_store_dwordx2 v230, v[250:251], s[64:65]
	ds_write_b128 v223, v[6:9]
	ds_write_b128 v223, v[2:5] offset:16
	ds_read_b128 v[6:9], v224
	ds_read_b128 v[2:5], v224 offset:1152
	s_waitcnt lgkmcnt(0)
	v_pk_add_f32 v[6:7], v[6:7], v[196:197]
	v_pk_add_f32 v[8:9], v[8:9], v[198:199]
	v_pk_add_f32 v[2:3], v[2:3], v[200:201]
	v_pk_add_f32 v[4:5], v[4:5], v[202:203]
	global_store_dwordx4 v227, v[6:9], s[16:17] offset:512
	global_store_dwordx4 v228, v[2:5], s[16:17] offset:512
	v_cvt_pk_bf16_f32 v248, v6, v7
	v_cvt_pk_bf16_f32 v249, v8, v9
	v_cvt_pk_bf16_f32 v250, v2, v3
	v_cvt_pk_bf16_f32 v251, v4, v5
	v_fmac_f32_e32 v231, v6, v6
	v_fmac_f32_e32 v232, v2, v2
	v_fmac_f32_e32 v231, v7, v7
	v_fmac_f32_e32 v232, v3, v3
	v_fmac_f32_e32 v231, v8, v8
	v_fmac_f32_e32 v232, v4, v4
	v_fmac_f32_e32 v231, v9, v9
	v_fmac_f32_e32 v232, v5, v5
	global_store_dwordx2 v229, v[248:249], s[64:65] offset:256
	global_store_dwordx2 v230, v[250:251], s[64:65] offset:256
	s_nop 1
	v_add_f32_dpp v231, v231, v231 quad_perm:[1,0,3,2] row_mask:0xf bank_mask:0xf
	v_add_f32_dpp v232, v232, v232 quad_perm:[1,0,3,2] row_mask:0xf bank_mask:0xf
	s_nop 0
	v_add_f32_dpp v231, v231, v231 quad_perm:[2,3,0,1] row_mask:0xf bank_mask:0xf
	v_add_f32_dpp v232, v232, v232 quad_perm:[2,3,0,1] row_mask:0xf bank_mask:0xf
	s_nop 0
	v_add_f32_dpp v231, v231, v231 row_half_mirror row_mask:0xf bank_mask:0xf
	v_add_f32_dpp v232, v232, v232 row_half_mirror row_mask:0xf bank_mask:0xf
	s_nop 0
	s_mov_b32 exec_lo, 0x1010101
	s_mov_b32 exec_hi, 0x1010101
	global_atomic_add_f32 v183, v231, s[10:11] offset:704
	global_atomic_add_f32 v183, v232, s[10:11] offset:736
	s_mov_b64 exec, -1
	s_andn2_b64 vcc, exec, s[4:5]
	s_mov_b64 s[4:5], -1
	s_cbranch_vccnz .LBB0_1816
	s_andn2_b64 vcc, exec, s[6:7]
	s_cbranch_vccnz .LBB0_1815
	s_barrier
	s_branch .LBB0_1815

; #define LAS __attribute__((address_space(3)))
; __global__ void __launch_bounds__(512, 2) fwd(Args a) {
;     extern __shared__ __attribute__((aligned(16))) unsigned char lds_raw[];
;     LAS unsigned char* lds = (LAS unsigned char*)lds_raw;
	.amdhsa_kernel _Z3fwd4Args
		.amdhsa_group_segment_fixed_size 18432
		.amdhsa_private_segment_fixed_size 0
		.amdhsa_kernarg_size 432
		.amdhsa_user_sgpr_count 2
		.amdhsa_user_sgpr_dispatch_ptr 0
		.amdhsa_user_sgpr_queue_ptr 0
		.amdhsa_user_sgpr_kernarg_segment_ptr 1
		.amdhsa_user_sgpr_dispatch_id 0
		.amdhsa_user_sgpr_kernarg_preload_length 0
		.amdhsa_user_sgpr_kernarg_preload_offset 0
		.amdhsa_user_sgpr_private_segment_size 0
		.amdhsa_uses_dynamic_stack 0
		.amdhsa_enable_private_segment 0
		.amdhsa_system_sgpr_workgroup_id_x 1
		.amdhsa_system_sgpr_workgroup_id_y 0
		.amdhsa_system_sgpr_workgroup_id_z 0
		.amdhsa_system_sgpr_workgroup_info 0
		.amdhsa_system_vgpr_workitem_id 0
		.amdhsa_next_free_vgpr 256
		.amdhsa_next_free_sgpr 102
		.amdhsa_accum_offset 256
		.amdhsa_reserve_vcc 1
		.amdhsa_float_round_mode_32 0
		.amdhsa_float_round_mode_16_64 0
		.amdhsa_float_denorm_mode_32 3
		.amdhsa_float_denorm_mode_16_64 3
		.amdhsa_dx10_clamp 1
		.amdhsa_ieee_mode 1
		.amdhsa_fp16_overflow 0
		.amdhsa_tg_split 0
		.amdhsa_exception_fp_ieee_invalid_op 0
		.amdhsa_exception_fp_denorm_src 0
		.amdhsa_exception_fp_ieee_div_zero 0
		.amdhsa_exception_fp_ieee_overflow 0
		.amdhsa_exception_fp_ieee_underflow 0
		.amdhsa_exception_fp_ieee_inexact 0
		.amdhsa_exception_int_div_zero 0
	.end_amdhsa_kernel

; #define LAS __attribute__((address_space(3)))
; __global__ void __launch_bounds__(512, 2) fwd(Args a) {
;     extern __shared__ __attribute__((aligned(16))) unsigned char lds_raw[];
;     LAS unsigned char* lds = (LAS unsigned char*)lds_raw;
amdhsa.kernels:
  - .agpr_count:     0
    .args:
      - .offset:         0
        .size:           176
        .value_kind:     by_value
      - .offset:         176
        .size:           4
        .value_kind:     hidden_block_count_x
      - .offset:         180
        .size:           4
        .value_kind:     hidden_block_count_y
      - .offset:         184
        .size:           4
        .value_kind:     hidden_block_count_z
      - .offset:         188
        .size:           2
        .value_kind:     hidden_group_size_x
      - .offset:         190
        .size:           2
        .value_kind:     hidden_group_size_y
      - .offset:         192
        .size:           2
        .value_kind:     hidden_group_size_z
      - .offset:         194
        .size:           2
        .value_kind:     hidden_remainder_x
      - .offset:         196
        .size:           2
        .value_kind:     hidden_remainder_y
      - .offset:         198
        .size:           2
        .value_kind:     hidden_remainder_z
      - .offset:         216
        .size:           8
        .value_kind:     hidden_global_offset_x
      - .offset:         224
        .size:           8
        .value_kind:     hidden_global_offset_y
      - .offset:         232
        .size:           8
        .value_kind:     hidden_global_offset_z
      - .offset:         240
        .size:           2
        .value_kind:     hidden_grid_dims
      - .offset:         296
        .size:           4
        .value_kind:     hidden_dynamic_lds_size
    .group_segment_fixed_size: 18432
    .kernarg_segment_align: 8
    .kernarg_segment_size: 432
    .language:       OpenCL C
    .language_version:
      - 2
      - 0
    .max_flat_workgroup_size: 512
    .name:           _Z3fwd4Args
    .private_segment_fixed_size: 0
    .sgpr_count:     108
    .sgpr_spill_count: 20
    .symbol:         _Z3fwd4Args.kd
    .uniform_work_group_size: 1
    .uses_dynamic_stack: false
    .vgpr_count:     256
    .vgpr_spill_count: 0
    .wavefront_size: 64
